# K-loop load segments rescheduled: all LDS fragment reads first, then LDS-DMA groups, scalar bookkeeping last (pure reorder), on top of v15
# baseline (speedup 1.0000x reference)
.LBB0_446:
	ds_read_b128 v[148:151], v165
	ds_read_b128 v[174:177], v165 offset:1024
	ds_read_b128 v[180:183], v165 offset:2048
	ds_read_b128 v[184:187], v165 offset:3072
	ds_read_b128 v[188:191], v169
	ds_read_b128 v[192:195], v169 offset:1024
	ds_read_b128 v[196:199], v169 offset:2048
	ds_read_b128 v[200:203], v169 offset:3072
	ds_read_b128 v[204:207], v173
	ds_read_b128 v[208:211], v173 offset:1024
	ds_read_b128 v[212:215], v173 offset:2048
	ds_read_b128 v[216:219], v173 offset:3072
	ds_read_b128 v[220:223], v173 offset:4096
	ds_read_b128 v[224:227], v173 offset:5120
	ds_read_b128 v[228:231], v173 offset:6144
	ds_read_b128 v[236:239], v173 offset:7168
	v_lshl_add_u64 v[154:155], s[4:5], 0, v[140:141]
	s_add_i32 m0, s7, 0xc000
	s_nop 0
	global_load_lds_dwordx4 v[154:155], off
	v_lshl_add_u64 v[154:155], s[4:5], 0, v[142:143]
	s_add_i32 m0, s7, 0xe000
	s_nop 0
	global_load_lds_dwordx4 v[154:155], off
	s_add_u32 s50, s4, 0xfff00080
	s_addc_u32 s51, s5, -1
	s_cmp_eq_u32 s68, 60
	s_cselect_b32 s53, s3, s51
	s_cselect_b32 s52, s8, s50
	s_cselect_b32 s51, s39, s65
	s_cselect_b32 s50, s45, s63
	s_setprio 1
	s_waitcnt vmcnt(8) lgkmcnt(0)
	s_barrier
	v_mfma_f32_16x16x32_bf16 v[126:129], v[148:151], v[204:207], v[126:129]
	v_mfma_f32_16x16x32_bf16 v[122:125], v[180:183], v[204:207], v[122:125]
	v_mfma_f32_16x16x32_bf16 v[110:113], v[148:151], v[212:215], v[110:113]
	v_mfma_f32_16x16x32_bf16 v[106:109], v[180:183], v[212:215], v[106:109]
	v_mfma_f32_16x16x32_bf16 v[94:97], v[148:151], v[220:223], v[94:97]
	v_mfma_f32_16x16x32_bf16 v[90:93], v[180:183], v[220:223], v[90:93]
	v_mfma_f32_16x16x32_bf16 v[78:81], v[148:151], v[228:231], v[78:81]
	v_mfma_f32_16x16x32_bf16 v[74:77], v[180:183], v[228:231], v[74:77]
	v_mfma_f32_16x16x32_bf16 v[126:129], v[174:177], v[208:211], v[126:129]
	v_mfma_f32_16x16x32_bf16 v[122:125], v[184:187], v[208:211], v[122:125]
	v_mfma_f32_16x16x32_bf16 v[110:113], v[174:177], v[216:219], v[110:113]
	v_mfma_f32_16x16x32_bf16 v[106:109], v[184:187], v[216:219], v[106:109]
	v_mfma_f32_16x16x32_bf16 v[94:97], v[174:177], v[224:227], v[94:97]
	v_mfma_f32_16x16x32_bf16 v[90:93], v[184:187], v[224:227], v[90:93]
	v_mfma_f32_16x16x32_bf16 v[78:81], v[174:177], v[236:239], v[78:81]
	v_mfma_f32_16x16x32_bf16 v[74:77], v[184:187], v[236:239], v[74:77]
	v_mfma_f32_16x16x32_bf16 v[118:121], v[188:191], v[204:207], v[118:121]
	v_mfma_f32_16x16x32_bf16 v[114:117], v[196:199], v[204:207], v[114:117]
	v_mfma_f32_16x16x32_bf16 v[102:105], v[188:191], v[212:215], v[102:105]
	v_mfma_f32_16x16x32_bf16 v[98:101], v[196:199], v[212:215], v[98:101]
	v_mfma_f32_16x16x32_bf16 v[86:89], v[188:191], v[220:223], v[86:89]
	v_mfma_f32_16x16x32_bf16 v[82:85], v[196:199], v[220:223], v[82:85]
	v_mfma_f32_16x16x32_bf16 v[70:73], v[188:191], v[228:231], v[70:73]
	v_mfma_f32_16x16x32_bf16 v[66:69], v[196:199], v[228:231], v[66:69]
	v_mfma_f32_16x16x32_bf16 v[118:121], v[192:195], v[208:211], v[118:121]
	v_mfma_f32_16x16x32_bf16 v[114:117], v[200:203], v[208:211], v[114:117]
	v_mfma_f32_16x16x32_bf16 v[102:105], v[192:195], v[216:219], v[102:105]
	v_mfma_f32_16x16x32_bf16 v[98:101], v[200:203], v[216:219], v[98:101]
	v_mfma_f32_16x16x32_bf16 v[86:89], v[192:195], v[224:227], v[86:89]
	v_mfma_f32_16x16x32_bf16 v[82:85], v[200:203], v[224:227], v[82:85]
	v_mfma_f32_16x16x32_bf16 v[70:73], v[192:195], v[236:239], v[70:73]
	v_mfma_f32_16x16x32_bf16 v[66:69], v[200:203], v[236:239], v[66:69]
	s_barrier
	s_setprio 0
	ds_read_b128 v[204:207], v173 offset:16384
	ds_read_b128 v[208:211], v173 offset:17408
	ds_read_b128 v[212:215], v173 offset:18432
	ds_read_b128 v[216:219], v173 offset:19456
	ds_read_b128 v[220:223], v173 offset:20480
	ds_read_b128 v[224:227], v173 offset:21504
	ds_read_b128 v[228:231], v173 offset:22528
	ds_read_b128 v[236:239], v173 offset:23552
	v_lshl_add_u64 v[154:155], s[50:51], 0, v[132:133]
	s_add_i32 s69, s59, s35
	s_mov_b32 m0, s69
	s_nop 0
	global_load_lds_dwordx4 v[154:155], off
	s_add_i32 m0, s69, 0x2000
	v_lshl_add_u64 v[158:159], s[50:51], 0, v[136:137]
	global_load_lds_dwordx4 v[158:159], off
	s_add_u32 s70, s50, 0x100000
	s_addc_u32 s71, s51, 0
	v_lshl_add_u64 v[162:163], s[70:71], 0, v[132:133]
	s_add_i32 s69, s60, s35
	s_mov_b32 m0, s69
	s_nop 0
	global_load_lds_dwordx4 v[162:163], off
	v_lshl_add_u64 v[162:163], s[70:71], 0, v[136:137]
	s_add_i32 m0, s69, 0x2000
	s_nop 0
	global_load_lds_dwordx4 v[162:163], off
	v_lshl_add_u64 v[162:163], s[52:53], 0, v[130:131]
	s_mov_b32 m0, s7
	s_nop 0
	global_load_lds_dwordx4 v[162:163], off
	v_lshl_add_u64 v[166:167], s[52:53], 0, v[134:135]
	s_mov_b32 m0, s37
	s_nop 0
	global_load_lds_dwordx4 v[166:167], off
	s_setprio 1
	s_waitcnt vmcnt(8) lgkmcnt(0)
	s_barrier
	v_mfma_f32_16x16x32_bf16 v[62:65], v[148:151], v[204:207], v[62:65]
	v_mfma_f32_16x16x32_bf16 v[58:61], v[180:183], v[204:207], v[58:61]
	v_mfma_f32_16x16x32_bf16 v[46:49], v[148:151], v[212:215], v[46:49]
	v_mfma_f32_16x16x32_bf16 v[42:45], v[180:183], v[212:215], v[42:45]
	v_mfma_f32_16x16x32_bf16 v[30:33], v[148:151], v[220:223], v[30:33]
	v_mfma_f32_16x16x32_bf16 v[26:29], v[180:183], v[220:223], v[26:29]
	v_mfma_f32_16x16x32_bf16 v[14:17], v[148:151], v[228:231], v[14:17]
	v_mfma_f32_16x16x32_bf16 v[10:13], v[180:183], v[228:231], v[10:13]
	v_mfma_f32_16x16x32_bf16 v[62:65], v[174:177], v[208:211], v[62:65]
	v_mfma_f32_16x16x32_bf16 v[58:61], v[184:187], v[208:211], v[58:61]
	v_mfma_f32_16x16x32_bf16 v[46:49], v[174:177], v[216:219], v[46:49]
	v_mfma_f32_16x16x32_bf16 v[42:45], v[184:187], v[216:219], v[42:45]
	v_mfma_f32_16x16x32_bf16 v[30:33], v[174:177], v[224:227], v[30:33]
	v_mfma_f32_16x16x32_bf16 v[26:29], v[184:187], v[224:227], v[26:29]
	v_mfma_f32_16x16x32_bf16 v[14:17], v[174:177], v[236:239], v[14:17]
	v_mfma_f32_16x16x32_bf16 v[10:13], v[184:187], v[236:239], v[10:13]
	v_mfma_f32_16x16x32_bf16 v[54:57], v[188:191], v[204:207], v[54:57]
	v_mfma_f32_16x16x32_bf16 v[50:53], v[196:199], v[204:207], v[50:53]
	v_mfma_f32_16x16x32_bf16 v[38:41], v[188:191], v[212:215], v[38:41]
	v_mfma_f32_16x16x32_bf16 v[34:37], v[196:199], v[212:215], v[34:37]
	v_mfma_f32_16x16x32_bf16 v[22:25], v[188:191], v[220:223], v[22:25]
	v_mfma_f32_16x16x32_bf16 v[18:21], v[196:199], v[220:223], v[18:21]
	v_mfma_f32_16x16x32_bf16 v[6:9], v[188:191], v[228:231], v[6:9]
	v_mfma_f32_16x16x32_bf16 v[2:5], v[196:199], v[228:231], v[2:5]
	v_mfma_f32_16x16x32_bf16 v[54:57], v[192:195], v[208:211], v[54:57]
	v_mfma_f32_16x16x32_bf16 v[50:53], v[200:203], v[208:211], v[50:53]
	v_mfma_f32_16x16x32_bf16 v[38:41], v[192:195], v[216:219], v[38:41]
	v_mfma_f32_16x16x32_bf16 v[34:37], v[200:203], v[216:219], v[34:37]
	v_mfma_f32_16x16x32_bf16 v[22:25], v[192:195], v[224:227], v[22:25]
	v_mfma_f32_16x16x32_bf16 v[18:21], v[200:203], v[224:227], v[18:21]
	v_mfma_f32_16x16x32_bf16 v[6:9], v[192:195], v[236:239], v[6:9]
	v_mfma_f32_16x16x32_bf16 v[2:5], v[200:203], v[236:239], v[2:5]
	s_barrier
	s_setprio 0
	s_add_i32 s69, 0, 0x18000
	v_add_u32_e32 v139, s69, v161
	ds_read_b128 v[148:151], v139
	ds_read_b128 v[174:177], v139 offset:1024
	ds_read_b128 v[180:183], v139 offset:2048
	ds_read_b128 v[184:187], v139 offset:3072
	s_add_i32 s70, 0, 0x1c000
	v_add_u32_e32 v139, s70, v161
	ds_read_b128 v[188:191], v139
	ds_read_b128 v[192:195], v139 offset:1024
	ds_read_b128 v[196:199], v139 offset:2048
	ds_read_b128 v[200:203], v139 offset:3072
	ds_read_b128 v[204:207], v173 offset:32768
	ds_read_b128 v[208:211], v173 offset:33792
	ds_read_b128 v[212:215], v173 offset:34816
	ds_read_b128 v[216:219], v173 offset:35840
	ds_read_b128 v[220:223], v173 offset:36864
	ds_read_b128 v[224:227], v173 offset:37888
	ds_read_b128 v[228:231], v173 offset:38912
	ds_read_b128 v[236:239], v173 offset:39936
	s_mov_b32 m0, s41
	s_add_u32 s52, s52, 0x100000
	s_addc_u32 s53, s53, 0
	v_lshl_add_u64 v[170:171], s[52:53], 0, v[130:131]
	global_load_lds_dwordx4 v[170:171], off
	v_lshl_add_u64 v[170:171], s[52:53], 0, v[134:135]
	s_mov_b32 m0, s43
	s_nop 0
	global_load_lds_dwordx4 v[170:171], off
	s_setprio 1
	s_waitcnt vmcnt(8) lgkmcnt(0)
	s_barrier
	v_mfma_f32_16x16x32_bf16 v[126:129], v[148:151], v[204:207], v[126:129]
	v_mfma_f32_16x16x32_bf16 v[122:125], v[180:183], v[204:207], v[122:125]
	v_mfma_f32_16x16x32_bf16 v[110:113], v[148:151], v[212:215], v[110:113]
	v_mfma_f32_16x16x32_bf16 v[106:109], v[180:183], v[212:215], v[106:109]
	v_mfma_f32_16x16x32_bf16 v[94:97], v[148:151], v[220:223], v[94:97]
	v_mfma_f32_16x16x32_bf16 v[90:93], v[180:183], v[220:223], v[90:93]
	v_mfma_f32_16x16x32_bf16 v[78:81], v[148:151], v[228:231], v[78:81]
	v_mfma_f32_16x16x32_bf16 v[74:77], v[180:183], v[228:231], v[74:77]
	v_mfma_f32_16x16x32_bf16 v[126:129], v[174:177], v[208:211], v[126:129]
	v_mfma_f32_16x16x32_bf16 v[122:125], v[184:187], v[208:211], v[122:125]
	v_mfma_f32_16x16x32_bf16 v[110:113], v[174:177], v[216:219], v[110:113]
	v_mfma_f32_16x16x32_bf16 v[106:109], v[184:187], v[216:219], v[106:109]
	v_mfma_f32_16x16x32_bf16 v[94:97], v[174:177], v[224:227], v[94:97]
	v_mfma_f32_16x16x32_bf16 v[90:93], v[184:187], v[224:227], v[90:93]
	v_mfma_f32_16x16x32_bf16 v[78:81], v[174:177], v[236:239], v[78:81]
	v_mfma_f32_16x16x32_bf16 v[74:77], v[184:187], v[236:239], v[74:77]
	v_mfma_f32_16x16x32_bf16 v[118:121], v[188:191], v[204:207], v[118:121]
	v_mfma_f32_16x16x32_bf16 v[114:117], v[196:199], v[204:207], v[114:117]
	v_mfma_f32_16x16x32_bf16 v[102:105], v[188:191], v[212:215], v[102:105]
	v_mfma_f32_16x16x32_bf16 v[98:101], v[196:199], v[212:215], v[98:101]
	v_mfma_f32_16x16x32_bf16 v[86:89], v[188:191], v[220:223], v[86:89]
	v_mfma_f32_16x16x32_bf16 v[82:85], v[196:199], v[220:223], v[82:85]
	v_mfma_f32_16x16x32_bf16 v[70:73], v[188:191], v[228:231], v[70:73]
	v_mfma_f32_16x16x32_bf16 v[66:69], v[196:199], v[228:231], v[66:69]
	v_mfma_f32_16x16x32_bf16 v[118:121], v[192:195], v[208:211], v[118:121]
	v_mfma_f32_16x16x32_bf16 v[114:117], v[200:203], v[208:211], v[114:117]
	v_mfma_f32_16x16x32_bf16 v[102:105], v[192:195], v[216:219], v[102:105]
	v_mfma_f32_16x16x32_bf16 v[98:101], v[200:203], v[216:219], v[98:101]
	v_mfma_f32_16x16x32_bf16 v[86:89], v[192:195], v[224:227], v[86:89]
	v_mfma_f32_16x16x32_bf16 v[82:85], v[200:203], v[224:227], v[82:85]
	v_mfma_f32_16x16x32_bf16 v[70:73], v[192:195], v[236:239], v[70:73]
	v_mfma_f32_16x16x32_bf16 v[66:69], v[200:203], v[236:239], v[66:69]
	s_barrier
	s_setprio 0
	ds_read_b128 v[204:207], v173 offset:49152
	ds_read_b128 v[208:211], v173 offset:50176
	ds_read_b128 v[212:215], v173 offset:51200
	ds_read_b128 v[216:219], v173 offset:52224
	ds_read_b128 v[220:223], v173 offset:53248
	ds_read_b128 v[224:227], v173 offset:54272
	ds_read_b128 v[228:231], v173 offset:55296
	ds_read_b128 v[236:239], v173 offset:56320
	v_lshl_add_u64 v[154:155], v[154:155], 0, s[16:17]
	s_add_i32 s52, s69, s35
	s_mov_b32 m0, s52
	s_nop 0
	global_load_lds_dwordx4 v[154:155], off
	s_add_i32 m0, s52, 0x2000
	v_lshl_add_u64 v[154:155], v[158:159], 0, s[16:17]
	global_load_lds_dwordx4 v[154:155], off
	s_add_u32 s50, s50, 0x100080
	s_addc_u32 s51, s51, 0
	v_lshl_add_u64 v[154:155], s[50:51], 0, v[132:133]
	s_add_i32 s52, s70, s35
	s_mov_b32 m0, s52
	s_nop 0
	global_load_lds_dwordx4 v[154:155], off
	v_lshl_add_u64 v[154:155], s[50:51], 0, v[136:137]
	s_add_i32 m0, s52, 0x2000
	s_nop 0
	global_load_lds_dwordx4 v[154:155], off
	v_lshl_add_u64 v[154:155], v[162:163], 0, s[16:17]
	s_mov_b32 m0, s57
	s_nop 0
	global_load_lds_dwordx4 v[154:155], off
	v_lshl_add_u64 v[154:155], v[166:167], 0, s[16:17]
	s_mov_b32 m0, s58
	s_nop 0
	global_load_lds_dwordx4 v[154:155], off
	s_setprio 1
	s_waitcnt vmcnt(8) lgkmcnt(0)
	s_barrier
	v_mfma_f32_16x16x32_bf16 v[62:65], v[148:151], v[204:207], v[62:65]
	v_mfma_f32_16x16x32_bf16 v[58:61], v[180:183], v[204:207], v[58:61]
	v_mfma_f32_16x16x32_bf16 v[46:49], v[148:151], v[212:215], v[46:49]
	v_mfma_f32_16x16x32_bf16 v[42:45], v[180:183], v[212:215], v[42:45]
	v_mfma_f32_16x16x32_bf16 v[30:33], v[148:151], v[220:223], v[30:33]
	v_mfma_f32_16x16x32_bf16 v[26:29], v[180:183], v[220:223], v[26:29]
	v_mfma_f32_16x16x32_bf16 v[14:17], v[148:151], v[228:231], v[14:17]
	v_mfma_f32_16x16x32_bf16 v[10:13], v[180:183], v[228:231], v[10:13]
	v_mfma_f32_16x16x32_bf16 v[62:65], v[174:177], v[208:211], v[62:65]
	v_mfma_f32_16x16x32_bf16 v[58:61], v[184:187], v[208:211], v[58:61]
	v_mfma_f32_16x16x32_bf16 v[46:49], v[174:177], v[216:219], v[46:49]
	v_mfma_f32_16x16x32_bf16 v[42:45], v[184:187], v[216:219], v[42:45]
	v_mfma_f32_16x16x32_bf16 v[30:33], v[174:177], v[224:227], v[30:33]
	v_mfma_f32_16x16x32_bf16 v[26:29], v[184:187], v[224:227], v[26:29]
	v_mfma_f32_16x16x32_bf16 v[14:17], v[174:177], v[236:239], v[14:17]
	v_mfma_f32_16x16x32_bf16 v[10:13], v[184:187], v[236:239], v[10:13]
	v_mfma_f32_16x16x32_bf16 v[54:57], v[188:191], v[204:207], v[54:57]
	v_mfma_f32_16x16x32_bf16 v[50:53], v[196:199], v[204:207], v[50:53]
	v_mfma_f32_16x16x32_bf16 v[38:41], v[188:191], v[212:215], v[38:41]
	v_mfma_f32_16x16x32_bf16 v[34:37], v[196:199], v[212:215], v[34:37]
	v_mfma_f32_16x16x32_bf16 v[22:25], v[188:191], v[220:223], v[22:25]
	v_mfma_f32_16x16x32_bf16 v[18:21], v[196:199], v[220:223], v[18:21]
	v_mfma_f32_16x16x32_bf16 v[6:9], v[188:191], v[228:231], v[6:9]
	v_mfma_f32_16x16x32_bf16 v[2:5], v[196:199], v[228:231], v[2:5]
	v_mfma_f32_16x16x32_bf16 v[54:57], v[192:195], v[208:211], v[54:57]
	v_mfma_f32_16x16x32_bf16 v[50:53], v[200:203], v[208:211], v[50:53]
	v_mfma_f32_16x16x32_bf16 v[38:41], v[192:195], v[216:219], v[38:41]
	v_mfma_f32_16x16x32_bf16 v[34:37], v[200:203], v[216:219], v[34:37]
	v_mfma_f32_16x16x32_bf16 v[22:25], v[192:195], v[224:227], v[22:25]
	v_mfma_f32_16x16x32_bf16 v[18:21], v[200:203], v[224:227], v[18:21]
	v_mfma_f32_16x16x32_bf16 v[6:9], v[192:195], v[236:239], v[6:9]
	v_mfma_f32_16x16x32_bf16 v[2:5], v[200:203], v[236:239], v[2:5]
	s_barrier
	s_setprio 0
	s_add_i32 s68, s68, 2
	s_add_u32 s4, s4, 0x100
	s_addc_u32 s5, s5, 0
	s_add_u32 s63, s63, 0x100
	s_addc_u32 s65, s65, 0
	s_cmp_gt_u32 s68, 61
	s_cbranch_scc0 .LBB0_446
	s_and_b64 vcc, exec, s[20:21]
	s_cbranch_vccz .LBB0_449
	s_barrier

.LBB0_668:
	ds_read_b128 v[154:157], v151
	ds_read_b128 v[158:161], v151 offset:1024
	ds_read_b128 v[162:165], v151 offset:2048
	ds_read_b128 v[166:169], v151 offset:3072
	ds_read_b128 v[170:173], v152
	ds_read_b128 v[174:177], v152 offset:1024
	ds_read_b128 v[178:181], v152 offset:2048
	ds_read_b128 v[182:185], v152 offset:3072
	ds_read_b128 v[186:189], v153
	ds_read_b128 v[190:193], v153 offset:1024
	ds_read_b128 v[194:197], v153 offset:2048
	ds_read_b128 v[198:201], v153 offset:3072
	ds_read_b128 v[202:205], v153 offset:4096
	ds_read_b128 v[206:209], v153 offset:5120
	ds_read_b128 v[210:213], v153 offset:6144
	ds_read_b128 v[214:217], v153 offset:7168
	v_lshl_add_u64 v[148:149], s[34:35], 0, v[140:141]
	s_add_i32 m0, s31, 0xc000
	s_nop 0
	global_load_lds_dwordx4 v[148:149], off
	v_lshl_add_u64 v[148:149], s[34:35], 0, v[142:143]
	s_add_i32 m0, s31, 0xe000
	s_nop 0
	global_load_lds_dwordx4 v[148:149], off
	s_add_u32 s36, s34, 0xfff00080
	s_addc_u32 s37, s35, -1
	s_cmp_eq_u32 s68, 60
	s_cselect_b32 s39, s25, s37
	s_cselect_b32 s38, s61, s36
	s_cselect_b32 s37, s23, s65
	s_cselect_b32 s36, s62, s63
	s_setprio 1
	s_waitcnt vmcnt(8) lgkmcnt(0)
	s_barrier
	v_mfma_f32_16x16x32_bf16 v[126:129], v[154:157], v[186:189], v[126:129]
	v_mfma_f32_16x16x32_bf16 v[122:125], v[162:165], v[186:189], v[122:125]
	v_mfma_f32_16x16x32_bf16 v[114:117], v[154:157], v[194:197], v[114:117]
	v_mfma_f32_16x16x32_bf16 v[106:109], v[162:165], v[194:197], v[106:109]
	v_mfma_f32_16x16x32_bf16 v[98:101], v[154:157], v[202:205], v[98:101]
	v_mfma_f32_16x16x32_bf16 v[90:93], v[162:165], v[202:205], v[90:93]
	v_mfma_f32_16x16x32_bf16 v[82:85], v[154:157], v[210:213], v[82:85]
	v_mfma_f32_16x16x32_bf16 v[74:77], v[162:165], v[210:213], v[74:77]
	v_mfma_f32_16x16x32_bf16 v[126:129], v[158:161], v[190:193], v[126:129]
	v_mfma_f32_16x16x32_bf16 v[122:125], v[166:169], v[190:193], v[122:125]
	v_mfma_f32_16x16x32_bf16 v[114:117], v[158:161], v[198:201], v[114:117]
	v_mfma_f32_16x16x32_bf16 v[106:109], v[166:169], v[198:201], v[106:109]
	v_mfma_f32_16x16x32_bf16 v[98:101], v[158:161], v[206:209], v[98:101]
	v_mfma_f32_16x16x32_bf16 v[90:93], v[166:169], v[206:209], v[90:93]
	v_mfma_f32_16x16x32_bf16 v[82:85], v[158:161], v[214:217], v[82:85]
	v_mfma_f32_16x16x32_bf16 v[74:77], v[166:169], v[214:217], v[74:77]
	v_mfma_f32_16x16x32_bf16 v[118:121], v[170:173], v[186:189], v[118:121]
	v_mfma_f32_16x16x32_bf16 v[110:113], v[178:181], v[186:189], v[110:113]
	v_mfma_f32_16x16x32_bf16 v[102:105], v[170:173], v[194:197], v[102:105]
	v_mfma_f32_16x16x32_bf16 v[94:97], v[178:181], v[194:197], v[94:97]
	v_mfma_f32_16x16x32_bf16 v[86:89], v[170:173], v[202:205], v[86:89]
	v_mfma_f32_16x16x32_bf16 v[78:81], v[178:181], v[202:205], v[78:81]
	v_mfma_f32_16x16x32_bf16 v[70:73], v[170:173], v[210:213], v[70:73]
	v_mfma_f32_16x16x32_bf16 v[66:69], v[178:181], v[210:213], v[66:69]
	v_mfma_f32_16x16x32_bf16 v[118:121], v[174:177], v[190:193], v[118:121]
	v_mfma_f32_16x16x32_bf16 v[110:113], v[182:185], v[190:193], v[110:113]
	v_mfma_f32_16x16x32_bf16 v[102:105], v[174:177], v[198:201], v[102:105]
	v_mfma_f32_16x16x32_bf16 v[94:97], v[182:185], v[198:201], v[94:97]
	v_mfma_f32_16x16x32_bf16 v[86:89], v[174:177], v[206:209], v[86:89]
	v_mfma_f32_16x16x32_bf16 v[78:81], v[182:185], v[206:209], v[78:81]
	v_mfma_f32_16x16x32_bf16 v[70:73], v[174:177], v[214:217], v[70:73]
	v_mfma_f32_16x16x32_bf16 v[66:69], v[182:185], v[214:217], v[66:69]
	s_barrier
	s_setprio 0
	ds_read_b128 v[186:189], v153 offset:16384
	ds_read_b128 v[190:193], v153 offset:17408
	ds_read_b128 v[194:197], v153 offset:18432
	ds_read_b128 v[198:201], v153 offset:19456
	ds_read_b128 v[202:205], v153 offset:20480
	ds_read_b128 v[206:209], v153 offset:21504
	ds_read_b128 v[210:213], v153 offset:22528
	ds_read_b128 v[214:217], v153 offset:23552
	v_lshl_add_u64 v[148:149], s[36:37], 0, v[136:137]
	s_add_i32 s69, s54, s47
	s_mov_b32 m0, s69
	s_nop 0
	global_load_lds_dwordx4 v[148:149], off
	s_add_i32 m0, s69, 0x2000
	v_lshl_add_u64 v[218:219], s[36:37], 0, v[132:133]
	global_load_lds_dwordx4 v[218:219], off
	s_add_u32 s70, s36, 0x100000
	s_addc_u32 s71, s37, 0
	v_lshl_add_u64 v[220:221], s[70:71], 0, v[136:137]
	s_add_i32 s69, s55, s47
	s_mov_b32 m0, s69
	s_nop 0
	global_load_lds_dwordx4 v[220:221], off
	v_lshl_add_u64 v[220:221], s[70:71], 0, v[132:133]
	s_add_i32 m0, s69, 0x2000
	s_nop 0
	global_load_lds_dwordx4 v[220:221], off
	v_lshl_add_u64 v[220:221], s[38:39], 0, v[138:139]
	s_mov_b32 m0, s31
	s_nop 0
	global_load_lds_dwordx4 v[220:221], off
	v_lshl_add_u64 v[222:223], s[38:39], 0, v[134:135]
	s_mov_b32 m0, s48
	s_nop 0
	global_load_lds_dwordx4 v[222:223], off
	s_setprio 1
	s_waitcnt vmcnt(8) lgkmcnt(0)
	s_barrier
	v_mfma_f32_16x16x32_bf16 v[62:65], v[154:157], v[186:189], v[62:65]
	v_mfma_f32_16x16x32_bf16 v[58:61], v[162:165], v[186:189], v[58:61]
	v_mfma_f32_16x16x32_bf16 v[50:53], v[154:157], v[194:197], v[50:53]
	v_mfma_f32_16x16x32_bf16 v[42:45], v[162:165], v[194:197], v[42:45]
	v_mfma_f32_16x16x32_bf16 v[34:37], v[154:157], v[202:205], v[34:37]
	v_mfma_f32_16x16x32_bf16 v[26:29], v[162:165], v[202:205], v[26:29]
	v_mfma_f32_16x16x32_bf16 v[18:21], v[154:157], v[210:213], v[18:21]
	v_mfma_f32_16x16x32_bf16 v[10:13], v[162:165], v[210:213], v[10:13]
	v_mfma_f32_16x16x32_bf16 v[62:65], v[158:161], v[190:193], v[62:65]
	v_mfma_f32_16x16x32_bf16 v[58:61], v[166:169], v[190:193], v[58:61]
	v_mfma_f32_16x16x32_bf16 v[50:53], v[158:161], v[198:201], v[50:53]
	v_mfma_f32_16x16x32_bf16 v[42:45], v[166:169], v[198:201], v[42:45]
	v_mfma_f32_16x16x32_bf16 v[34:37], v[158:161], v[206:209], v[34:37]
	v_mfma_f32_16x16x32_bf16 v[26:29], v[166:169], v[206:209], v[26:29]
	v_mfma_f32_16x16x32_bf16 v[18:21], v[158:161], v[214:217], v[18:21]
	v_mfma_f32_16x16x32_bf16 v[10:13], v[166:169], v[214:217], v[10:13]
	v_mfma_f32_16x16x32_bf16 v[54:57], v[170:173], v[186:189], v[54:57]
	v_mfma_f32_16x16x32_bf16 v[46:49], v[178:181], v[186:189], v[46:49]
	v_mfma_f32_16x16x32_bf16 v[38:41], v[170:173], v[194:197], v[38:41]
	v_mfma_f32_16x16x32_bf16 v[30:33], v[178:181], v[194:197], v[30:33]
	v_mfma_f32_16x16x32_bf16 v[22:25], v[170:173], v[202:205], v[22:25]
	v_mfma_f32_16x16x32_bf16 v[14:17], v[178:181], v[202:205], v[14:17]
	v_mfma_f32_16x16x32_bf16 v[6:9], v[170:173], v[210:213], v[6:9]
	v_mfma_f32_16x16x32_bf16 v[2:5], v[178:181], v[210:213], v[2:5]
	v_mfma_f32_16x16x32_bf16 v[54:57], v[174:177], v[190:193], v[54:57]
	v_mfma_f32_16x16x32_bf16 v[46:49], v[182:185], v[190:193], v[46:49]
	v_mfma_f32_16x16x32_bf16 v[38:41], v[174:177], v[198:201], v[38:41]
	v_mfma_f32_16x16x32_bf16 v[30:33], v[182:185], v[198:201], v[30:33]
	v_mfma_f32_16x16x32_bf16 v[22:25], v[174:177], v[206:209], v[22:25]
	v_mfma_f32_16x16x32_bf16 v[14:17], v[182:185], v[206:209], v[14:17]
	v_mfma_f32_16x16x32_bf16 v[6:9], v[174:177], v[214:217], v[6:9]
	v_mfma_f32_16x16x32_bf16 v[2:5], v[182:185], v[214:217], v[2:5]
	s_barrier
	s_setprio 0
	s_add_i32 s69, 0, 0x18000
	v_add_u32_e32 v166, s69, v131
	ds_read_b128 v[154:157], v166
	ds_read_b128 v[158:161], v166 offset:1024
	ds_read_b128 v[162:165], v166 offset:2048
	ds_read_b128 v[166:169], v166 offset:3072
	s_add_i32 s70, 0, 0x1c000
	v_add_u32_e32 v182, s70, v131
	ds_read_b128 v[170:173], v182
	ds_read_b128 v[174:177], v182 offset:1024
	ds_read_b128 v[178:181], v182 offset:2048
	ds_read_b128 v[182:185], v182 offset:3072
	ds_read_b128 v[186:189], v153 offset:32768
	ds_read_b128 v[190:193], v153 offset:33792
	ds_read_b128 v[194:197], v153 offset:34816
	ds_read_b128 v[198:201], v153 offset:35840
	ds_read_b128 v[202:205], v153 offset:36864
	ds_read_b128 v[206:209], v153 offset:37888
	ds_read_b128 v[210:213], v153 offset:38912
	ds_read_b128 v[214:217], v153 offset:39936
	s_mov_b32 m0, s49
	s_add_u32 s38, s38, 0x100000
	s_addc_u32 s39, s39, 0
	v_lshl_add_u64 v[224:225], s[38:39], 0, v[138:139]
	global_load_lds_dwordx4 v[224:225], off
	v_lshl_add_u64 v[224:225], s[38:39], 0, v[134:135]
	s_mov_b32 m0, s50
	s_nop 0
	global_load_lds_dwordx4 v[224:225], off
	s_setprio 1
	s_waitcnt vmcnt(8) lgkmcnt(0)
	s_barrier
	v_mfma_f32_16x16x32_bf16 v[126:129], v[154:157], v[186:189], v[126:129]
	v_mfma_f32_16x16x32_bf16 v[122:125], v[162:165], v[186:189], v[122:125]
	v_mfma_f32_16x16x32_bf16 v[114:117], v[154:157], v[194:197], v[114:117]
	v_mfma_f32_16x16x32_bf16 v[106:109], v[162:165], v[194:197], v[106:109]
	v_mfma_f32_16x16x32_bf16 v[98:101], v[154:157], v[202:205], v[98:101]
	v_mfma_f32_16x16x32_bf16 v[90:93], v[162:165], v[202:205], v[90:93]
	v_mfma_f32_16x16x32_bf16 v[82:85], v[154:157], v[210:213], v[82:85]
	v_mfma_f32_16x16x32_bf16 v[74:77], v[162:165], v[210:213], v[74:77]
	v_mfma_f32_16x16x32_bf16 v[126:129], v[158:161], v[190:193], v[126:129]
	v_mfma_f32_16x16x32_bf16 v[122:125], v[166:169], v[190:193], v[122:125]
	v_mfma_f32_16x16x32_bf16 v[114:117], v[158:161], v[198:201], v[114:117]
	v_mfma_f32_16x16x32_bf16 v[106:109], v[166:169], v[198:201], v[106:109]
	v_mfma_f32_16x16x32_bf16 v[98:101], v[158:161], v[206:209], v[98:101]
	v_mfma_f32_16x16x32_bf16 v[90:93], v[166:169], v[206:209], v[90:93]
	v_mfma_f32_16x16x32_bf16 v[82:85], v[158:161], v[214:217], v[82:85]
	v_mfma_f32_16x16x32_bf16 v[74:77], v[166:169], v[214:217], v[74:77]
	v_mfma_f32_16x16x32_bf16 v[118:121], v[170:173], v[186:189], v[118:121]
	v_mfma_f32_16x16x32_bf16 v[110:113], v[178:181], v[186:189], v[110:113]
	v_mfma_f32_16x16x32_bf16 v[102:105], v[170:173], v[194:197], v[102:105]
	v_mfma_f32_16x16x32_bf16 v[94:97], v[178:181], v[194:197], v[94:97]
	v_mfma_f32_16x16x32_bf16 v[86:89], v[170:173], v[202:205], v[86:89]
	v_mfma_f32_16x16x32_bf16 v[78:81], v[178:181], v[202:205], v[78:81]
	v_mfma_f32_16x16x32_bf16 v[70:73], v[170:173], v[210:213], v[70:73]
	v_mfma_f32_16x16x32_bf16 v[66:69], v[178:181], v[210:213], v[66:69]
	v_mfma_f32_16x16x32_bf16 v[118:121], v[174:177], v[190:193], v[118:121]
	v_mfma_f32_16x16x32_bf16 v[110:113], v[182:185], v[190:193], v[110:113]
	v_mfma_f32_16x16x32_bf16 v[102:105], v[174:177], v[198:201], v[102:105]
	v_mfma_f32_16x16x32_bf16 v[94:97], v[182:185], v[198:201], v[94:97]
	v_mfma_f32_16x16x32_bf16 v[86:89], v[174:177], v[206:209], v[86:89]
	v_mfma_f32_16x16x32_bf16 v[78:81], v[182:185], v[206:209], v[78:81]
	v_mfma_f32_16x16x32_bf16 v[70:73], v[174:177], v[214:217], v[70:73]
	v_mfma_f32_16x16x32_bf16 v[66:69], v[182:185], v[214:217], v[66:69]
	s_barrier
	s_setprio 0
	ds_read_b128 v[186:189], v153 offset:49152
	ds_read_b128 v[190:193], v153 offset:50176
	ds_read_b128 v[194:197], v153 offset:51200
	ds_read_b128 v[198:201], v153 offset:52224
	ds_read_b128 v[202:205], v153 offset:53248
	ds_read_b128 v[206:209], v153 offset:54272
	ds_read_b128 v[210:213], v153 offset:55296
	ds_read_b128 v[214:217], v153 offset:56320
	v_lshl_add_u64 v[148:149], v[148:149], 0, s[8:9]
	s_add_i32 s38, s69, s47
	s_mov_b32 m0, s38
	s_nop 0
	global_load_lds_dwordx4 v[148:149], off
	s_add_i32 m0, s38, 0x2000
	v_lshl_add_u64 v[148:149], v[218:219], 0, s[8:9]
	global_load_lds_dwordx4 v[148:149], off
	s_add_u32 s36, s36, 0x100080
	s_addc_u32 s37, s37, 0
	v_lshl_add_u64 v[148:149], s[36:37], 0, v[136:137]
	s_add_i32 s38, s70, s47
	s_mov_b32 m0, s38
	s_nop 0
	global_load_lds_dwordx4 v[148:149], off
	v_lshl_add_u64 v[148:149], s[36:37], 0, v[132:133]
	s_add_i32 m0, s38, 0x2000
	s_nop 0
	global_load_lds_dwordx4 v[148:149], off
	v_lshl_add_u64 v[148:149], v[220:221], 0, s[8:9]
	s_mov_b32 m0, s52
	s_nop 0
	global_load_lds_dwordx4 v[148:149], off
	v_lshl_add_u64 v[148:149], v[222:223], 0, s[8:9]
	s_mov_b32 m0, s53
	s_nop 0
	global_load_lds_dwordx4 v[148:149], off
	s_setprio 1
	s_waitcnt vmcnt(8) lgkmcnt(0)
	s_barrier
	v_mfma_f32_16x16x32_bf16 v[62:65], v[154:157], v[186:189], v[62:65]
	v_mfma_f32_16x16x32_bf16 v[58:61], v[162:165], v[186:189], v[58:61]
	v_mfma_f32_16x16x32_bf16 v[50:53], v[154:157], v[194:197], v[50:53]
	v_mfma_f32_16x16x32_bf16 v[42:45], v[162:165], v[194:197], v[42:45]
	v_mfma_f32_16x16x32_bf16 v[34:37], v[154:157], v[202:205], v[34:37]
	v_mfma_f32_16x16x32_bf16 v[26:29], v[162:165], v[202:205], v[26:29]
	v_mfma_f32_16x16x32_bf16 v[18:21], v[154:157], v[210:213], v[18:21]
	v_mfma_f32_16x16x32_bf16 v[10:13], v[162:165], v[210:213], v[10:13]
	v_mfma_f32_16x16x32_bf16 v[62:65], v[158:161], v[190:193], v[62:65]
	v_mfma_f32_16x16x32_bf16 v[58:61], v[166:169], v[190:193], v[58:61]
	v_mfma_f32_16x16x32_bf16 v[50:53], v[158:161], v[198:201], v[50:53]
	v_mfma_f32_16x16x32_bf16 v[42:45], v[166:169], v[198:201], v[42:45]
	v_mfma_f32_16x16x32_bf16 v[34:37], v[158:161], v[206:209], v[34:37]
	v_mfma_f32_16x16x32_bf16 v[26:29], v[166:169], v[206:209], v[26:29]
	v_mfma_f32_16x16x32_bf16 v[18:21], v[158:161], v[214:217], v[18:21]
	v_mfma_f32_16x16x32_bf16 v[10:13], v[166:169], v[214:217], v[10:13]
	v_mfma_f32_16x16x32_bf16 v[54:57], v[170:173], v[186:189], v[54:57]
	v_mfma_f32_16x16x32_bf16 v[46:49], v[178:181], v[186:189], v[46:49]
	v_mfma_f32_16x16x32_bf16 v[38:41], v[170:173], v[194:197], v[38:41]
	v_mfma_f32_16x16x32_bf16 v[30:33], v[178:181], v[194:197], v[30:33]
	v_mfma_f32_16x16x32_bf16 v[22:25], v[170:173], v[202:205], v[22:25]
	v_mfma_f32_16x16x32_bf16 v[14:17], v[178:181], v[202:205], v[14:17]
	v_mfma_f32_16x16x32_bf16 v[6:9], v[170:173], v[210:213], v[6:9]
	v_mfma_f32_16x16x32_bf16 v[2:5], v[178:181], v[210:213], v[2:5]
	v_mfma_f32_16x16x32_bf16 v[54:57], v[174:177], v[190:193], v[54:57]
	v_mfma_f32_16x16x32_bf16 v[46:49], v[182:185], v[190:193], v[46:49]
	v_mfma_f32_16x16x32_bf16 v[38:41], v[174:177], v[198:201], v[38:41]
	v_mfma_f32_16x16x32_bf16 v[30:33], v[182:185], v[198:201], v[30:33]
	v_mfma_f32_16x16x32_bf16 v[22:25], v[174:177], v[206:209], v[22:25]
	v_mfma_f32_16x16x32_bf16 v[14:17], v[182:185], v[206:209], v[14:17]
	v_mfma_f32_16x16x32_bf16 v[6:9], v[174:177], v[214:217], v[6:9]
	v_mfma_f32_16x16x32_bf16 v[2:5], v[182:185], v[214:217], v[2:5]
	s_barrier
	s_setprio 0
	s_add_i32 s68, s68, 2
	s_add_u32 s34, s34, 0x100
	s_addc_u32 s35, s35, 0
	s_add_u32 s63, s63, 0x100
	s_addc_u32 s65, s65, 0
	s_cmp_gt_u32 s68, 61
	s_cbranch_scc0 .LBB0_668
	s_and_b64 vcc, exec, s[12:13]
	s_cbranch_vccz .LBB0_671
	s_barrier

.LBB0_845:
	ds_read_b128 v[130:133], v238
	ds_read_b128 v[134:137], v238 offset:1024
	ds_read_b128 v[138:141], v238 offset:2048
	ds_read_b128 v[142:145], v238 offset:3072
	ds_read_b128 v[146:149], v239
	ds_read_b128 v[150:153], v239 offset:1024
	ds_read_b128 v[154:157], v239 offset:2048
	ds_read_b128 v[158:161], v239 offset:3072
	ds_read_b128 v[162:165], v240
	ds_read_b128 v[166:169], v240 offset:1024
	ds_read_b128 v[170:173], v240 offset:2048
	ds_read_b128 v[174:177], v240 offset:3072
	ds_read_b128 v[178:181], v240 offset:4096
	ds_read_b128 v[182:185], v240 offset:5120
	ds_read_b128 v[186:189], v240 offset:6144
	ds_read_b128 v[190:193], v240 offset:7168
	v_lshl_add_u64 v[194:195], s[2:3], 0, v[210:211]
	s_add_i32 m0, s55, 0xc000
	s_nop 0
	global_load_lds_dwordx4 v[194:195], off
	v_lshl_add_u64 v[194:195], s[2:3], 0, v[212:213]
	s_add_i32 m0, s55, 0xe000
	s_nop 0
	global_load_lds_dwordx4 v[194:195], off
	s_add_u32 s56, s2, 0x100
	s_addc_u32 s57, s3, 0
	s_cmp_eq_u32 s92, 28
	s_cselect_b32 s61, s49, s57
	s_cselect_b32 s60, s88, s56
	s_cselect_b32 s59, s47, s91
	s_cselect_b32 s58, s89, s90
	s_setprio 1
	s_waitcnt vmcnt(8) lgkmcnt(0)
	s_barrier
	v_mfma_i32_16x16x64_i8 v[126:129], v[130:133], v[162:165], v[126:129]
	v_mfma_i32_16x16x64_i8 v[122:125], v[138:141], v[162:165], v[122:125]
	v_mfma_i32_16x16x64_i8 v[118:121], v[130:133], v[170:173], v[118:121]
	v_mfma_i32_16x16x64_i8 v[110:113], v[138:141], v[170:173], v[110:113]
	v_mfma_i32_16x16x64_i8 v[78:81], v[130:133], v[178:181], v[78:81]
	v_mfma_i32_16x16x64_i8 v[30:33], v[138:141], v[178:181], v[30:33]
	v_mfma_i32_16x16x64_i8 v[74:77], v[130:133], v[186:189], v[74:77]
	v_mfma_i32_16x16x64_i8 v[26:29], v[138:141], v[186:189], v[26:29]
	v_mfma_i32_16x16x64_i8 v[126:129], v[134:137], v[166:169], v[126:129]
	v_mfma_i32_16x16x64_i8 v[122:125], v[142:145], v[166:169], v[122:125]
	v_mfma_i32_16x16x64_i8 v[118:121], v[134:137], v[174:177], v[118:121]
	v_mfma_i32_16x16x64_i8 v[110:113], v[142:145], v[174:177], v[110:113]
	v_mfma_i32_16x16x64_i8 v[78:81], v[134:137], v[182:185], v[78:81]
	v_mfma_i32_16x16x64_i8 v[30:33], v[142:145], v[182:185], v[30:33]
	v_mfma_i32_16x16x64_i8 v[74:77], v[134:137], v[190:193], v[74:77]
	v_mfma_i32_16x16x64_i8 v[26:29], v[142:145], v[190:193], v[26:29]
	v_mfma_i32_16x16x64_i8 v[102:105], v[146:149], v[162:165], v[102:105]
	v_mfma_i32_16x16x64_i8 v[98:101], v[154:157], v[162:165], v[98:101]
	v_mfma_i32_16x16x64_i8 v[94:97], v[146:149], v[170:173], v[94:97]
	v_mfma_i32_16x16x64_i8 v[90:93], v[154:157], v[170:173], v[90:93]
	v_mfma_i32_16x16x64_i8 v[70:73], v[146:149], v[178:181], v[70:73]
	v_mfma_i32_16x16x64_i8 v[22:25], v[154:157], v[178:181], v[22:25]
	v_mfma_i32_16x16x64_i8 v[66:69], v[146:149], v[186:189], v[66:69]
	v_mfma_i32_16x16x64_i8 v[18:21], v[154:157], v[186:189], v[18:21]
	v_mfma_i32_16x16x64_i8 v[102:105], v[150:153], v[166:169], v[102:105]
	v_mfma_i32_16x16x64_i8 v[98:101], v[158:161], v[166:169], v[98:101]
	v_mfma_i32_16x16x64_i8 v[94:97], v[150:153], v[174:177], v[94:97]
	v_mfma_i32_16x16x64_i8 v[90:93], v[158:161], v[174:177], v[90:93]
	v_mfma_i32_16x16x64_i8 v[70:73], v[150:153], v[182:185], v[70:73]
	v_mfma_i32_16x16x64_i8 v[22:25], v[158:161], v[182:185], v[22:25]
	v_mfma_i32_16x16x64_i8 v[66:69], v[150:153], v[190:193], v[66:69]
	v_mfma_i32_16x16x64_i8 v[18:21], v[158:161], v[190:193], v[18:21]
	s_barrier
	s_setprio 0
	ds_read_b128 v[162:165], v240 offset:16384
	ds_read_b128 v[166:169], v240 offset:17408
	ds_read_b128 v[170:173], v240 offset:18432
	ds_read_b128 v[174:177], v240 offset:19456
	ds_read_b128 v[178:181], v240 offset:20480
	ds_read_b128 v[182:185], v240 offset:21504
	ds_read_b128 v[186:189], v240 offset:22528
	ds_read_b128 v[190:193], v240 offset:23552
	v_lshl_add_u64 v[194:195], s[58:59], 0, v[206:207]
	s_add_i32 s2, s84, s65
	s_mov_b32 m0, s2
	s_nop 0
	global_load_lds_dwordx4 v[194:195], off
	s_add_i32 m0, s2, 0x2000
	v_lshl_add_u64 v[196:197], s[58:59], 0, v[202:203]
	global_load_lds_dwordx4 v[196:197], off
	s_add_u32 s2, s58, 0x80000
	s_addc_u32 s3, s59, 0
	v_lshl_add_u64 v[198:199], s[2:3], 0, v[206:207]
	s_add_i32 s93, s85, s65
	s_mov_b32 m0, s93
	s_nop 0
	global_load_lds_dwordx4 v[198:199], off
	v_lshl_add_u64 v[198:199], s[2:3], 0, v[202:203]
	s_add_i32 m0, s93, 0x2000
	s_nop 0
	global_load_lds_dwordx4 v[198:199], off
	v_lshl_add_u64 v[198:199], s[60:61], 0, v[208:209]
	s_mov_b32 m0, s55
	s_nop 0
	global_load_lds_dwordx4 v[198:199], off
	v_lshl_add_u64 v[200:201], s[60:61], 0, v[204:205]
	s_mov_b32 m0, s69
	s_nop 0
	global_load_lds_dwordx4 v[200:201], off
	s_setprio 1
	s_waitcnt vmcnt(8) lgkmcnt(0)
	s_barrier
	v_mfma_i32_16x16x64_i8 v[62:65], v[130:133], v[162:165], v[62:65]
	v_mfma_i32_16x16x64_i8 v[14:17], v[138:141], v[162:165], v[14:17]
	v_mfma_i32_16x16x64_i8 v[58:61], v[130:133], v[170:173], v[58:61]
	v_mfma_i32_16x16x64_i8 v[10:13], v[138:141], v[170:173], v[10:13]
	v_mfma_i32_16x16x64_i8 v[114:117], v[130:133], v[178:181], v[114:117]
	v_mfma_i32_16x16x64_i8 v[106:109], v[138:141], v[178:181], v[106:109]
	v_mfma_i32_16x16x64_i8 v[86:89], v[130:133], v[186:189], v[86:89]
	v_mfma_i32_16x16x64_i8 v[82:85], v[138:141], v[186:189], v[82:85]
	v_mfma_i32_16x16x64_i8 v[62:65], v[134:137], v[166:169], v[62:65]
	v_mfma_i32_16x16x64_i8 v[14:17], v[142:145], v[166:169], v[14:17]
	v_mfma_i32_16x16x64_i8 v[58:61], v[134:137], v[174:177], v[58:61]
	v_mfma_i32_16x16x64_i8 v[10:13], v[142:145], v[174:177], v[10:13]
	v_mfma_i32_16x16x64_i8 v[114:117], v[134:137], v[182:185], v[114:117]
	v_mfma_i32_16x16x64_i8 v[106:109], v[142:145], v[182:185], v[106:109]
	v_mfma_i32_16x16x64_i8 v[86:89], v[134:137], v[190:193], v[86:89]
	v_mfma_i32_16x16x64_i8 v[82:85], v[142:145], v[190:193], v[82:85]
	v_mfma_i32_16x16x64_i8 v[50:53], v[146:149], v[162:165], v[50:53]
	v_mfma_i32_16x16x64_i8 v[6:9], v[154:157], v[162:165], v[6:9]
	v_mfma_i32_16x16x64_i8 v[42:45], v[146:149], v[170:173], v[42:45]
	v_mfma_i32_16x16x64_i8 v[2:5], v[154:157], v[170:173], v[2:5]
	v_mfma_i32_16x16x64_i8 v[54:57], v[146:149], v[178:181], v[54:57]
	v_mfma_i32_16x16x64_i8 v[46:49], v[154:157], v[178:181], v[46:49]
	v_mfma_i32_16x16x64_i8 v[38:41], v[146:149], v[186:189], v[38:41]
	v_mfma_i32_16x16x64_i8 v[34:37], v[154:157], v[186:189], v[34:37]
	v_mfma_i32_16x16x64_i8 v[50:53], v[150:153], v[166:169], v[50:53]
	v_mfma_i32_16x16x64_i8 v[6:9], v[158:161], v[166:169], v[6:9]
	v_mfma_i32_16x16x64_i8 v[42:45], v[150:153], v[174:177], v[42:45]
	v_mfma_i32_16x16x64_i8 v[2:5], v[158:161], v[174:177], v[2:5]
	v_mfma_i32_16x16x64_i8 v[54:57], v[150:153], v[182:185], v[54:57]
	v_mfma_i32_16x16x64_i8 v[46:49], v[158:161], v[182:185], v[46:49]
	v_mfma_i32_16x16x64_i8 v[38:41], v[150:153], v[190:193], v[38:41]
	v_mfma_i32_16x16x64_i8 v[34:37], v[158:161], v[190:193], v[34:37]
	s_barrier
	s_setprio 0
	s_add_i32 s93, 0, 0x18000
	v_add_u32_e32 v142, s93, v237
	ds_read_b128 v[130:133], v142
	ds_read_b128 v[134:137], v142 offset:1024
	ds_read_b128 v[138:141], v142 offset:2048
	ds_read_b128 v[142:145], v142 offset:3072
	s_add_i32 s94, 0, 0x1c000
	v_add_u32_e32 v158, s94, v237
	ds_read_b128 v[146:149], v158
	ds_read_b128 v[150:153], v158 offset:1024
	ds_read_b128 v[154:157], v158 offset:2048
	ds_read_b128 v[158:161], v158 offset:3072
	ds_read_b128 v[162:165], v240 offset:32768
	ds_read_b128 v[166:169], v240 offset:33792
	ds_read_b128 v[170:173], v240 offset:34816
	ds_read_b128 v[174:177], v240 offset:35840
	ds_read_b128 v[178:181], v240 offset:36864
	ds_read_b128 v[182:185], v240 offset:37888
	ds_read_b128 v[186:189], v240 offset:38912
	ds_read_b128 v[190:193], v240 offset:39936
	s_mov_b32 m0, s70
	s_add_u32 s2, s60, 0x4000
	s_addc_u32 s3, s61, 0
	v_lshl_add_u64 v[220:221], s[2:3], 0, v[208:209]
	global_load_lds_dwordx4 v[220:221], off
	v_lshl_add_u64 v[220:221], s[2:3], 0, v[204:205]
	s_mov_b32 m0, s71
	s_nop 0
	global_load_lds_dwordx4 v[220:221], off
	s_setprio 1
	s_waitcnt vmcnt(8) lgkmcnt(0)
	s_barrier
	v_mfma_i32_16x16x64_i8 v[126:129], v[130:133], v[162:165], v[126:129]
	v_mfma_i32_16x16x64_i8 v[122:125], v[138:141], v[162:165], v[122:125]
	v_mfma_i32_16x16x64_i8 v[118:121], v[130:133], v[170:173], v[118:121]
	v_mfma_i32_16x16x64_i8 v[110:113], v[138:141], v[170:173], v[110:113]
	v_mfma_i32_16x16x64_i8 v[78:81], v[130:133], v[178:181], v[78:81]
	v_mfma_i32_16x16x64_i8 v[30:33], v[138:141], v[178:181], v[30:33]
	v_mfma_i32_16x16x64_i8 v[74:77], v[130:133], v[186:189], v[74:77]
	v_mfma_i32_16x16x64_i8 v[26:29], v[138:141], v[186:189], v[26:29]
	v_mfma_i32_16x16x64_i8 v[126:129], v[134:137], v[166:169], v[126:129]
	v_mfma_i32_16x16x64_i8 v[122:125], v[142:145], v[166:169], v[122:125]
	v_mfma_i32_16x16x64_i8 v[118:121], v[134:137], v[174:177], v[118:121]
	v_mfma_i32_16x16x64_i8 v[110:113], v[142:145], v[174:177], v[110:113]
	v_mfma_i32_16x16x64_i8 v[78:81], v[134:137], v[182:185], v[78:81]
	v_mfma_i32_16x16x64_i8 v[30:33], v[142:145], v[182:185], v[30:33]
	v_mfma_i32_16x16x64_i8 v[74:77], v[134:137], v[190:193], v[74:77]
	v_mfma_i32_16x16x64_i8 v[26:29], v[142:145], v[190:193], v[26:29]
	v_mfma_i32_16x16x64_i8 v[102:105], v[146:149], v[162:165], v[102:105]
	v_mfma_i32_16x16x64_i8 v[98:101], v[154:157], v[162:165], v[98:101]
	v_mfma_i32_16x16x64_i8 v[94:97], v[146:149], v[170:173], v[94:97]
	v_mfma_i32_16x16x64_i8 v[90:93], v[154:157], v[170:173], v[90:93]
	v_mfma_i32_16x16x64_i8 v[70:73], v[146:149], v[178:181], v[70:73]
	v_mfma_i32_16x16x64_i8 v[22:25], v[154:157], v[178:181], v[22:25]
	v_mfma_i32_16x16x64_i8 v[66:69], v[146:149], v[186:189], v[66:69]
	v_mfma_i32_16x16x64_i8 v[18:21], v[154:157], v[186:189], v[18:21]
	v_mfma_i32_16x16x64_i8 v[102:105], v[150:153], v[166:169], v[102:105]
	v_mfma_i32_16x16x64_i8 v[98:101], v[158:161], v[166:169], v[98:101]
	v_mfma_i32_16x16x64_i8 v[94:97], v[150:153], v[174:177], v[94:97]
	v_mfma_i32_16x16x64_i8 v[90:93], v[158:161], v[174:177], v[90:93]
	v_mfma_i32_16x16x64_i8 v[70:73], v[150:153], v[182:185], v[70:73]
	v_mfma_i32_16x16x64_i8 v[22:25], v[158:161], v[182:185], v[22:25]
	v_mfma_i32_16x16x64_i8 v[66:69], v[150:153], v[190:193], v[66:69]
	v_mfma_i32_16x16x64_i8 v[18:21], v[158:161], v[190:193], v[18:21]
	s_barrier
	s_setprio 0
	ds_read_b128 v[162:165], v240 offset:49152
	ds_read_b128 v[166:169], v240 offset:50176
	ds_read_b128 v[170:173], v240 offset:51200
	ds_read_b128 v[174:177], v240 offset:52224
	ds_read_b128 v[178:181], v240 offset:53248
	ds_read_b128 v[182:185], v240 offset:54272
	ds_read_b128 v[186:189], v240 offset:55296
	ds_read_b128 v[190:193], v240 offset:56320
	v_lshl_add_u64 v[194:195], v[194:195], 0, s[36:37]
	s_add_i32 s2, s93, s65
	s_mov_b32 m0, s2
	s_nop 0
	global_load_lds_dwordx4 v[194:195], off
	s_add_i32 m0, s2, 0x2000
	v_lshl_add_u64 v[194:195], v[196:197], 0, s[36:37]
	global_load_lds_dwordx4 v[194:195], off
	s_add_u32 s2, s58, 0x80080
	s_addc_u32 s3, s59, 0
	v_lshl_add_u64 v[194:195], s[2:3], 0, v[206:207]
	s_add_i32 s58, s94, s65
	s_mov_b32 m0, s58
	s_nop 0
	global_load_lds_dwordx4 v[194:195], off
	v_lshl_add_u64 v[194:195], s[2:3], 0, v[202:203]
	s_add_i32 m0, s58, 0x2000
	s_nop 0
	global_load_lds_dwordx4 v[194:195], off
	v_lshl_add_u64 v[194:195], v[198:199], 0, s[36:37]
	s_mov_b32 m0, s78
	s_nop 0
	global_load_lds_dwordx4 v[194:195], off
	v_lshl_add_u64 v[194:195], v[200:201], 0, s[36:37]
	s_mov_b32 m0, s79
	s_nop 0
	global_load_lds_dwordx4 v[194:195], off
	s_setprio 1
	s_waitcnt vmcnt(8) lgkmcnt(0)
	s_barrier
	v_mfma_i32_16x16x64_i8 v[62:65], v[130:133], v[162:165], v[62:65]
	v_mfma_i32_16x16x64_i8 v[14:17], v[138:141], v[162:165], v[14:17]
	v_mfma_i32_16x16x64_i8 v[58:61], v[130:133], v[170:173], v[58:61]
	v_mfma_i32_16x16x64_i8 v[10:13], v[138:141], v[170:173], v[10:13]
	v_mfma_i32_16x16x64_i8 v[114:117], v[130:133], v[178:181], v[114:117]
	v_mfma_i32_16x16x64_i8 v[106:109], v[138:141], v[178:181], v[106:109]
	v_mfma_i32_16x16x64_i8 v[86:89], v[130:133], v[186:189], v[86:89]
	v_mfma_i32_16x16x64_i8 v[82:85], v[138:141], v[186:189], v[82:85]
	v_mfma_i32_16x16x64_i8 v[62:65], v[134:137], v[166:169], v[62:65]
	v_mfma_i32_16x16x64_i8 v[14:17], v[142:145], v[166:169], v[14:17]
	v_mfma_i32_16x16x64_i8 v[58:61], v[134:137], v[174:177], v[58:61]
	v_mfma_i32_16x16x64_i8 v[10:13], v[142:145], v[174:177], v[10:13]
	v_mfma_i32_16x16x64_i8 v[114:117], v[134:137], v[182:185], v[114:117]
	v_mfma_i32_16x16x64_i8 v[106:109], v[142:145], v[182:185], v[106:109]
	v_mfma_i32_16x16x64_i8 v[86:89], v[134:137], v[190:193], v[86:89]
	v_mfma_i32_16x16x64_i8 v[82:85], v[142:145], v[190:193], v[82:85]
	v_mfma_i32_16x16x64_i8 v[50:53], v[146:149], v[162:165], v[50:53]
	v_mfma_i32_16x16x64_i8 v[6:9], v[154:157], v[162:165], v[6:9]
	v_mfma_i32_16x16x64_i8 v[42:45], v[146:149], v[170:173], v[42:45]
	v_mfma_i32_16x16x64_i8 v[2:5], v[154:157], v[170:173], v[2:5]
	v_mfma_i32_16x16x64_i8 v[54:57], v[146:149], v[178:181], v[54:57]
	v_mfma_i32_16x16x64_i8 v[46:49], v[154:157], v[178:181], v[46:49]
	v_mfma_i32_16x16x64_i8 v[38:41], v[146:149], v[186:189], v[38:41]
	v_mfma_i32_16x16x64_i8 v[34:37], v[154:157], v[186:189], v[34:37]
	v_mfma_i32_16x16x64_i8 v[50:53], v[150:153], v[166:169], v[50:53]
	v_mfma_i32_16x16x64_i8 v[6:9], v[158:161], v[166:169], v[6:9]
	v_mfma_i32_16x16x64_i8 v[42:45], v[150:153], v[174:177], v[42:45]
	v_mfma_i32_16x16x64_i8 v[2:5], v[158:161], v[174:177], v[2:5]
	v_mfma_i32_16x16x64_i8 v[54:57], v[150:153], v[182:185], v[54:57]
	v_mfma_i32_16x16x64_i8 v[46:49], v[158:161], v[182:185], v[46:49]
	v_mfma_i32_16x16x64_i8 v[38:41], v[150:153], v[190:193], v[38:41]
	v_mfma_i32_16x16x64_i8 v[34:37], v[158:161], v[190:193], v[34:37]
	s_barrier
	s_setprio 0
	s_add_i32 s92, s92, 2
	s_add_u32 s90, s90, 0x100
	s_addc_u32 s91, s91, 0
	s_cmp_gt_u32 s92, 29
	s_mov_b64 s[2:3], s[56:57]
	s_cbranch_scc0 .LBB0_845
	s_and_b64 vcc, exec, s[38:39]
	s_cbranch_vccz .LBB0_848
	s_barrier

.LBB0_1099:
	ds_read_b128 v[130:133], v167
	ds_read_b128 v[134:137], v167 offset:1024
	ds_read_b128 v[138:141], v167 offset:2048
	ds_read_b128 v[142:145], v167 offset:3072
	ds_read_b128 v[170:173], v168
	ds_read_b128 v[174:177], v168 offset:1024
	ds_read_b128 v[178:181], v168 offset:2048
	ds_read_b128 v[182:185], v168 offset:3072
	ds_read_b128 v[186:189], v169
	ds_read_b128 v[190:193], v169 offset:1024
	ds_read_b128 v[194:197], v169 offset:2048
	ds_read_b128 v[198:201], v169 offset:3072
	ds_read_b128 v[202:205], v169 offset:4096
	ds_read_b128 v[206:209], v169 offset:5120
	ds_read_b128 v[210:213], v169 offset:6144
	ds_read_b128 v[214:217], v169 offset:7168
	v_lshl_add_u64 v[162:163], s[28:29], 0, v[154:155]
	s_add_i32 m0, s47, 0xc000
	s_nop 0
	global_load_lds_dwordx4 v[162:163], off
	v_lshl_add_u64 v[162:163], s[28:29], 0, v[156:157]
	s_add_i32 m0, s47, 0xe000
	s_nop 0
	global_load_lds_dwordx4 v[162:163], off
	s_add_u32 s30, s28, 0x100
	s_addc_u32 s31, s29, 0
	s_cmpk_eq_i32 s72, 0x52
	s_cselect_b32 s37, s3, s31
	s_cselect_b32 s36, s2, s30
	s_cselect_b32 s35, s27, s71
	s_cselect_b32 s34, s26, s70
	s_setprio 1
	s_waitcnt vmcnt(8) lgkmcnt(0)
	s_barrier
	v_mfma_i32_16x16x64_i8 v[126:129], v[130:133], v[186:189], v[126:129]
	v_mfma_i32_16x16x64_i8 v[122:125], v[138:141], v[186:189], v[122:125]
	v_mfma_i32_16x16x64_i8 v[110:113], v[130:133], v[194:197], v[110:113]
	v_mfma_i32_16x16x64_i8 v[106:109], v[138:141], v[194:197], v[106:109]
	v_mfma_i32_16x16x64_i8 v[94:97], v[130:133], v[202:205], v[94:97]
	v_mfma_i32_16x16x64_i8 v[90:93], v[138:141], v[202:205], v[90:93]
	v_mfma_i32_16x16x64_i8 v[78:81], v[130:133], v[210:213], v[78:81]
	v_mfma_i32_16x16x64_i8 v[74:77], v[138:141], v[210:213], v[74:77]
	v_mfma_i32_16x16x64_i8 v[126:129], v[134:137], v[190:193], v[126:129]
	v_mfma_i32_16x16x64_i8 v[122:125], v[142:145], v[190:193], v[122:125]
	v_mfma_i32_16x16x64_i8 v[110:113], v[134:137], v[198:201], v[110:113]
	v_mfma_i32_16x16x64_i8 v[106:109], v[142:145], v[198:201], v[106:109]
	v_mfma_i32_16x16x64_i8 v[94:97], v[134:137], v[206:209], v[94:97]
	v_mfma_i32_16x16x64_i8 v[90:93], v[142:145], v[206:209], v[90:93]
	v_mfma_i32_16x16x64_i8 v[78:81], v[134:137], v[214:217], v[78:81]
	v_mfma_i32_16x16x64_i8 v[74:77], v[142:145], v[214:217], v[74:77]
	v_mfma_i32_16x16x64_i8 v[118:121], v[170:173], v[186:189], v[118:121]
	v_mfma_i32_16x16x64_i8 v[114:117], v[178:181], v[186:189], v[114:117]
	v_mfma_i32_16x16x64_i8 v[102:105], v[170:173], v[194:197], v[102:105]
	v_mfma_i32_16x16x64_i8 v[98:101], v[178:181], v[194:197], v[98:101]
	v_mfma_i32_16x16x64_i8 v[86:89], v[170:173], v[202:205], v[86:89]
	v_mfma_i32_16x16x64_i8 v[82:85], v[178:181], v[202:205], v[82:85]
	v_mfma_i32_16x16x64_i8 v[70:73], v[170:173], v[210:213], v[70:73]
	v_mfma_i32_16x16x64_i8 v[66:69], v[178:181], v[210:213], v[66:69]
	v_mfma_i32_16x16x64_i8 v[118:121], v[174:177], v[190:193], v[118:121]
	v_mfma_i32_16x16x64_i8 v[114:117], v[182:185], v[190:193], v[114:117]
	v_mfma_i32_16x16x64_i8 v[102:105], v[174:177], v[198:201], v[102:105]
	v_mfma_i32_16x16x64_i8 v[98:101], v[182:185], v[198:201], v[98:101]
	v_mfma_i32_16x16x64_i8 v[86:89], v[174:177], v[206:209], v[86:89]
	v_mfma_i32_16x16x64_i8 v[82:85], v[182:185], v[206:209], v[82:85]
	v_mfma_i32_16x16x64_i8 v[70:73], v[174:177], v[214:217], v[70:73]
	v_mfma_i32_16x16x64_i8 v[66:69], v[182:185], v[214:217], v[66:69]
	s_barrier
	s_setprio 0
	ds_read_b128 v[186:189], v169 offset:16384
	ds_read_b128 v[190:193], v169 offset:17408
	ds_read_b128 v[194:197], v169 offset:18432
	ds_read_b128 v[198:201], v169 offset:19456
	ds_read_b128 v[202:205], v169 offset:20480
	ds_read_b128 v[206:209], v169 offset:21504
	ds_read_b128 v[210:213], v169 offset:22528
	ds_read_b128 v[214:217], v169 offset:23552
	v_lshl_add_u64 v[162:163], s[34:35], 0, v[150:151]
	s_add_i32 s28, s56, s46
	s_mov_b32 m0, s28
	s_nop 0
	global_load_lds_dwordx4 v[162:163], off
	s_add_i32 m0, s28, 0x2000
	v_lshl_add_u64 v[218:219], s[34:35], 0, v[146:147]
	global_load_lds_dwordx4 v[218:219], off
	s_add_u32 s28, s34, 0x158000
	s_addc_u32 s29, s35, 0
	v_lshl_add_u64 v[220:221], s[28:29], 0, v[150:151]
	s_add_i32 s73, s57, s46
	s_mov_b32 m0, s73
	s_nop 0
	global_load_lds_dwordx4 v[220:221], off
	v_lshl_add_u64 v[220:221], s[28:29], 0, v[146:147]
	s_add_i32 m0, s73, 0x2000
	s_nop 0
	global_load_lds_dwordx4 v[220:221], off
	v_lshl_add_u64 v[220:221], s[36:37], 0, v[152:153]
	s_mov_b32 m0, s47
	s_nop 0
	global_load_lds_dwordx4 v[220:221], off
	v_lshl_add_u64 v[222:223], s[36:37], 0, v[148:149]
	s_mov_b32 m0, s48
	s_nop 0
	global_load_lds_dwordx4 v[222:223], off
	s_setprio 1
	s_waitcnt vmcnt(8) lgkmcnt(0)
	s_barrier
	v_mfma_i32_16x16x64_i8 v[62:65], v[130:133], v[186:189], v[62:65]
	v_mfma_i32_16x16x64_i8 v[58:61], v[138:141], v[186:189], v[58:61]
	v_mfma_i32_16x16x64_i8 v[46:49], v[130:133], v[194:197], v[46:49]
	v_mfma_i32_16x16x64_i8 v[42:45], v[138:141], v[194:197], v[42:45]
	v_mfma_i32_16x16x64_i8 v[30:33], v[130:133], v[202:205], v[30:33]
	v_mfma_i32_16x16x64_i8 v[26:29], v[138:141], v[202:205], v[26:29]
	v_mfma_i32_16x16x64_i8 v[14:17], v[130:133], v[210:213], v[14:17]
	v_mfma_i32_16x16x64_i8 v[10:13], v[138:141], v[210:213], v[10:13]
	v_mfma_i32_16x16x64_i8 v[62:65], v[134:137], v[190:193], v[62:65]
	v_mfma_i32_16x16x64_i8 v[58:61], v[142:145], v[190:193], v[58:61]
	v_mfma_i32_16x16x64_i8 v[46:49], v[134:137], v[198:201], v[46:49]
	v_mfma_i32_16x16x64_i8 v[42:45], v[142:145], v[198:201], v[42:45]
	v_mfma_i32_16x16x64_i8 v[30:33], v[134:137], v[206:209], v[30:33]
	v_mfma_i32_16x16x64_i8 v[26:29], v[142:145], v[206:209], v[26:29]
	v_mfma_i32_16x16x64_i8 v[14:17], v[134:137], v[214:217], v[14:17]
	v_mfma_i32_16x16x64_i8 v[10:13], v[142:145], v[214:217], v[10:13]
	v_mfma_i32_16x16x64_i8 v[54:57], v[170:173], v[186:189], v[54:57]
	v_mfma_i32_16x16x64_i8 v[50:53], v[178:181], v[186:189], v[50:53]
	v_mfma_i32_16x16x64_i8 v[38:41], v[170:173], v[194:197], v[38:41]
	v_mfma_i32_16x16x64_i8 v[34:37], v[178:181], v[194:197], v[34:37]
	v_mfma_i32_16x16x64_i8 v[22:25], v[170:173], v[202:205], v[22:25]
	v_mfma_i32_16x16x64_i8 v[18:21], v[178:181], v[202:205], v[18:21]
	v_mfma_i32_16x16x64_i8 v[6:9], v[170:173], v[210:213], v[6:9]
	v_mfma_i32_16x16x64_i8 v[2:5], v[178:181], v[210:213], v[2:5]
	v_mfma_i32_16x16x64_i8 v[54:57], v[174:177], v[190:193], v[54:57]
	v_mfma_i32_16x16x64_i8 v[50:53], v[182:185], v[190:193], v[50:53]
	v_mfma_i32_16x16x64_i8 v[38:41], v[174:177], v[198:201], v[38:41]
	v_mfma_i32_16x16x64_i8 v[34:37], v[182:185], v[198:201], v[34:37]
	v_mfma_i32_16x16x64_i8 v[22:25], v[174:177], v[206:209], v[22:25]
	v_mfma_i32_16x16x64_i8 v[18:21], v[182:185], v[206:209], v[18:21]
	v_mfma_i32_16x16x64_i8 v[6:9], v[174:177], v[214:217], v[6:9]
	v_mfma_i32_16x16x64_i8 v[2:5], v[182:185], v[214:217], v[2:5]
	s_barrier
	s_setprio 0
	s_add_i32 s73, 0, 0x18000
	v_add_u32_e32 v142, s73, v166
	ds_read_b128 v[130:133], v142
	ds_read_b128 v[134:137], v142 offset:1024
	ds_read_b128 v[138:141], v142 offset:2048
	ds_read_b128 v[142:145], v142 offset:3072
	s_add_i32 s74, 0, 0x1c000
	v_add_u32_e32 v182, s74, v166
	ds_read_b128 v[170:173], v182
	ds_read_b128 v[174:177], v182 offset:1024
	ds_read_b128 v[178:181], v182 offset:2048
	ds_read_b128 v[182:185], v182 offset:3072
	ds_read_b128 v[186:189], v169 offset:32768
	ds_read_b128 v[190:193], v169 offset:33792
	ds_read_b128 v[194:197], v169 offset:34816
	ds_read_b128 v[198:201], v169 offset:35840
	ds_read_b128 v[202:205], v169 offset:36864
	ds_read_b128 v[206:209], v169 offset:37888
	ds_read_b128 v[210:213], v169 offset:38912
	ds_read_b128 v[214:217], v169 offset:39936
	s_mov_b32 m0, s49
	s_add_u32 s28, s36, 0x158000
	s_addc_u32 s29, s37, 0
	v_lshl_add_u64 v[224:225], s[28:29], 0, v[152:153]
	global_load_lds_dwordx4 v[224:225], off
	v_lshl_add_u64 v[224:225], s[28:29], 0, v[148:149]
	s_mov_b32 m0, s50
	s_nop 0
	global_load_lds_dwordx4 v[224:225], off
	s_setprio 1
	s_waitcnt vmcnt(8) lgkmcnt(0)
	s_barrier
	v_mfma_i32_16x16x64_i8 v[126:129], v[130:133], v[186:189], v[126:129]
	v_mfma_i32_16x16x64_i8 v[122:125], v[138:141], v[186:189], v[122:125]
	v_mfma_i32_16x16x64_i8 v[110:113], v[130:133], v[194:197], v[110:113]
	v_mfma_i32_16x16x64_i8 v[106:109], v[138:141], v[194:197], v[106:109]
	v_mfma_i32_16x16x64_i8 v[94:97], v[130:133], v[202:205], v[94:97]
	v_mfma_i32_16x16x64_i8 v[90:93], v[138:141], v[202:205], v[90:93]
	v_mfma_i32_16x16x64_i8 v[78:81], v[130:133], v[210:213], v[78:81]
	v_mfma_i32_16x16x64_i8 v[74:77], v[138:141], v[210:213], v[74:77]
	v_mfma_i32_16x16x64_i8 v[126:129], v[134:137], v[190:193], v[126:129]
	v_mfma_i32_16x16x64_i8 v[122:125], v[142:145], v[190:193], v[122:125]
	v_mfma_i32_16x16x64_i8 v[110:113], v[134:137], v[198:201], v[110:113]
	v_mfma_i32_16x16x64_i8 v[106:109], v[142:145], v[198:201], v[106:109]
	v_mfma_i32_16x16x64_i8 v[94:97], v[134:137], v[206:209], v[94:97]
	v_mfma_i32_16x16x64_i8 v[90:93], v[142:145], v[206:209], v[90:93]
	v_mfma_i32_16x16x64_i8 v[78:81], v[134:137], v[214:217], v[78:81]
	v_mfma_i32_16x16x64_i8 v[74:77], v[142:145], v[214:217], v[74:77]
	v_mfma_i32_16x16x64_i8 v[118:121], v[170:173], v[186:189], v[118:121]
	v_mfma_i32_16x16x64_i8 v[114:117], v[178:181], v[186:189], v[114:117]
	v_mfma_i32_16x16x64_i8 v[102:105], v[170:173], v[194:197], v[102:105]
	v_mfma_i32_16x16x64_i8 v[98:101], v[178:181], v[194:197], v[98:101]
	v_mfma_i32_16x16x64_i8 v[86:89], v[170:173], v[202:205], v[86:89]
	v_mfma_i32_16x16x64_i8 v[82:85], v[178:181], v[202:205], v[82:85]
	v_mfma_i32_16x16x64_i8 v[70:73], v[170:173], v[210:213], v[70:73]
	v_mfma_i32_16x16x64_i8 v[66:69], v[178:181], v[210:213], v[66:69]
	v_mfma_i32_16x16x64_i8 v[118:121], v[174:177], v[190:193], v[118:121]
	v_mfma_i32_16x16x64_i8 v[114:117], v[182:185], v[190:193], v[114:117]
	v_mfma_i32_16x16x64_i8 v[102:105], v[174:177], v[198:201], v[102:105]
	v_mfma_i32_16x16x64_i8 v[98:101], v[182:185], v[198:201], v[98:101]
	v_mfma_i32_16x16x64_i8 v[86:89], v[174:177], v[206:209], v[86:89]
	v_mfma_i32_16x16x64_i8 v[82:85], v[182:185], v[206:209], v[82:85]
	v_mfma_i32_16x16x64_i8 v[70:73], v[174:177], v[214:217], v[70:73]
	v_mfma_i32_16x16x64_i8 v[66:69], v[182:185], v[214:217], v[66:69]
	s_barrier
	s_setprio 0
	ds_read_b128 v[186:189], v169 offset:49152
	ds_read_b128 v[190:193], v169 offset:50176
	ds_read_b128 v[194:197], v169 offset:51200
	ds_read_b128 v[198:201], v169 offset:52224
	ds_read_b128 v[202:205], v169 offset:53248
	ds_read_b128 v[206:209], v169 offset:54272
	ds_read_b128 v[210:213], v169 offset:55296
	ds_read_b128 v[214:217], v169 offset:56320
	v_lshl_add_u64 v[162:163], v[162:163], 0, s[14:15]
	s_add_i32 s28, s73, s46
	s_mov_b32 m0, s28
	s_nop 0
	global_load_lds_dwordx4 v[162:163], off
	s_add_i32 m0, s28, 0x2000
	v_lshl_add_u64 v[162:163], v[218:219], 0, s[14:15]
	global_load_lds_dwordx4 v[162:163], off
	s_add_u32 s28, s34, 0x158080
	s_addc_u32 s29, s35, 0
	v_lshl_add_u64 v[162:163], s[28:29], 0, v[150:151]
	s_add_i32 s34, s74, s46
	s_mov_b32 m0, s34
	s_nop 0
	global_load_lds_dwordx4 v[162:163], off
	v_lshl_add_u64 v[162:163], s[28:29], 0, v[146:147]
	s_add_i32 m0, s34, 0x2000
	s_nop 0
	global_load_lds_dwordx4 v[162:163], off
	v_lshl_add_u64 v[162:163], v[220:221], 0, s[14:15]
	s_mov_b32 m0, s54
	s_nop 0
	global_load_lds_dwordx4 v[162:163], off
	v_lshl_add_u64 v[162:163], v[222:223], 0, s[14:15]
	s_mov_b32 m0, s55
	s_nop 0
	global_load_lds_dwordx4 v[162:163], off
	s_setprio 1
	s_waitcnt vmcnt(8) lgkmcnt(0)
	s_barrier
	v_mfma_i32_16x16x64_i8 v[62:65], v[130:133], v[186:189], v[62:65]
	v_mfma_i32_16x16x64_i8 v[58:61], v[138:141], v[186:189], v[58:61]
	v_mfma_i32_16x16x64_i8 v[46:49], v[130:133], v[194:197], v[46:49]
	v_mfma_i32_16x16x64_i8 v[42:45], v[138:141], v[194:197], v[42:45]
	v_mfma_i32_16x16x64_i8 v[30:33], v[130:133], v[202:205], v[30:33]
	v_mfma_i32_16x16x64_i8 v[26:29], v[138:141], v[202:205], v[26:29]
	v_mfma_i32_16x16x64_i8 v[14:17], v[130:133], v[210:213], v[14:17]
	v_mfma_i32_16x16x64_i8 v[10:13], v[138:141], v[210:213], v[10:13]
	v_mfma_i32_16x16x64_i8 v[62:65], v[134:137], v[190:193], v[62:65]
	v_mfma_i32_16x16x64_i8 v[58:61], v[142:145], v[190:193], v[58:61]
	v_mfma_i32_16x16x64_i8 v[46:49], v[134:137], v[198:201], v[46:49]
	v_mfma_i32_16x16x64_i8 v[42:45], v[142:145], v[198:201], v[42:45]
	v_mfma_i32_16x16x64_i8 v[30:33], v[134:137], v[206:209], v[30:33]
	v_mfma_i32_16x16x64_i8 v[26:29], v[142:145], v[206:209], v[26:29]
	v_mfma_i32_16x16x64_i8 v[14:17], v[134:137], v[214:217], v[14:17]
	v_mfma_i32_16x16x64_i8 v[10:13], v[142:145], v[214:217], v[10:13]
	v_mfma_i32_16x16x64_i8 v[54:57], v[170:173], v[186:189], v[54:57]
	v_mfma_i32_16x16x64_i8 v[50:53], v[178:181], v[186:189], v[50:53]
	v_mfma_i32_16x16x64_i8 v[38:41], v[170:173], v[194:197], v[38:41]
	v_mfma_i32_16x16x64_i8 v[34:37], v[178:181], v[194:197], v[34:37]
	v_mfma_i32_16x16x64_i8 v[22:25], v[170:173], v[202:205], v[22:25]
	v_mfma_i32_16x16x64_i8 v[18:21], v[178:181], v[202:205], v[18:21]
	v_mfma_i32_16x16x64_i8 v[6:9], v[170:173], v[210:213], v[6:9]
	v_mfma_i32_16x16x64_i8 v[2:5], v[178:181], v[210:213], v[2:5]
	v_mfma_i32_16x16x64_i8 v[54:57], v[174:177], v[190:193], v[54:57]
	v_mfma_i32_16x16x64_i8 v[50:53], v[182:185], v[190:193], v[50:53]
	v_mfma_i32_16x16x64_i8 v[38:41], v[174:177], v[198:201], v[38:41]
	v_mfma_i32_16x16x64_i8 v[34:37], v[182:185], v[198:201], v[34:37]
	v_mfma_i32_16x16x64_i8 v[22:25], v[174:177], v[206:209], v[22:25]
	v_mfma_i32_16x16x64_i8 v[18:21], v[182:185], v[206:209], v[18:21]
	v_mfma_i32_16x16x64_i8 v[6:9], v[174:177], v[214:217], v[6:9]
	v_mfma_i32_16x16x64_i8 v[2:5], v[182:185], v[214:217], v[2:5]
	s_barrier
	s_setprio 0
	s_add_i32 s72, s72, 2
	s_add_u32 s70, s70, 0x100
	s_addc_u32 s71, s71, 0
	s_cmpk_gt_u32 s72, 0x53
	s_mov_b64 s[28:29], s[30:31]
	s_cbranch_scc0 .LBB0_1099
	s_and_b64 vcc, exec, s[16:17]
	s_cbranch_vccz .LBB0_1102
	s_barrier

.LBB0_1246:
	ds_read_b128 v[130:133], v193
	ds_read_b128 v[134:137], v193 offset:1024
	ds_read_b128 v[138:141], v193 offset:2048
	ds_read_b128 v[142:145], v193 offset:3072
	ds_read_b128 v[162:165], v194
	ds_read_b128 v[166:169], v194 offset:1024
	ds_read_b128 v[170:173], v194 offset:2048
	ds_read_b128 v[174:177], v194 offset:3072
	ds_read_b128 v[178:181], v195
	ds_read_b128 v[182:185], v195 offset:1024
	ds_read_b128 v[186:189], v195 offset:2048
	ds_read_b128 v[196:199], v195 offset:3072
	ds_read_b128 v[200:203], v195 offset:4096
	ds_read_b128 v[204:207], v195 offset:5120
	ds_read_b128 v[208:211], v195 offset:6144
	ds_read_b128 v[212:215], v195 offset:7168
	v_lshl_add_u64 v[216:217], s[28:29], 0, v[154:155]
	s_add_i32 m0, s45, 0xc000
	s_nop 0
	global_load_lds_dwordx4 v[216:217], off
	v_lshl_add_u64 v[216:217], s[28:29], 0, v[156:157]
	s_add_i32 m0, s45, 0xe000
	s_nop 0
	global_load_lds_dwordx4 v[216:217], off
	s_add_u32 s30, s28, 0xfff00080
	s_addc_u32 s31, s29, -1
	s_cmp_eq_u32 s68, 60
	s_cselect_b32 s35, s3, s31
	s_cselect_b32 s34, s23, s30
	s_cselect_b32 s31, s17, s65
	s_cselect_b32 s30, s62, s63
	s_setprio 1
	s_waitcnt vmcnt(8) lgkmcnt(0)
	s_barrier
	v_mfma_f32_16x16x32_bf16 v[126:129], v[130:133], v[178:181], v[126:129]
	v_mfma_f32_16x16x32_bf16 v[122:125], v[138:141], v[178:181], v[122:125]
	v_mfma_f32_16x16x32_bf16 v[118:121], v[130:133], v[186:189], v[118:121]
	v_mfma_f32_16x16x32_bf16 v[110:113], v[138:141], v[186:189], v[110:113]
	v_mfma_f32_16x16x32_bf16 v[98:101], v[130:133], v[200:203], v[98:101]
	v_mfma_f32_16x16x32_bf16 v[90:93], v[138:141], v[200:203], v[90:93]
	v_mfma_f32_16x16x32_bf16 v[82:85], v[130:133], v[208:211], v[82:85]
	v_mfma_f32_16x16x32_bf16 v[74:77], v[138:141], v[208:211], v[74:77]
	v_mfma_f32_16x16x32_bf16 v[126:129], v[134:137], v[182:185], v[126:129]
	v_mfma_f32_16x16x32_bf16 v[122:125], v[142:145], v[182:185], v[122:125]
	v_mfma_f32_16x16x32_bf16 v[118:121], v[134:137], v[196:199], v[118:121]
	v_mfma_f32_16x16x32_bf16 v[110:113], v[142:145], v[196:199], v[110:113]
	v_mfma_f32_16x16x32_bf16 v[98:101], v[134:137], v[204:207], v[98:101]
	v_mfma_f32_16x16x32_bf16 v[90:93], v[142:145], v[204:207], v[90:93]
	v_mfma_f32_16x16x32_bf16 v[82:85], v[134:137], v[212:215], v[82:85]
	v_mfma_f32_16x16x32_bf16 v[74:77], v[142:145], v[212:215], v[74:77]
	v_mfma_f32_16x16x32_bf16 v[114:117], v[162:165], v[178:181], v[114:117]
	v_mfma_f32_16x16x32_bf16 v[106:109], v[170:173], v[178:181], v[106:109]
	v_mfma_f32_16x16x32_bf16 v[102:105], v[162:165], v[186:189], v[102:105]
	v_mfma_f32_16x16x32_bf16 v[94:97], v[170:173], v[186:189], v[94:97]
	v_mfma_f32_16x16x32_bf16 v[86:89], v[162:165], v[200:203], v[86:89]
	v_mfma_f32_16x16x32_bf16 v[78:81], v[170:173], v[200:203], v[78:81]
	v_mfma_f32_16x16x32_bf16 v[70:73], v[162:165], v[208:211], v[70:73]
	v_mfma_f32_16x16x32_bf16 v[66:69], v[170:173], v[208:211], v[66:69]
	v_mfma_f32_16x16x32_bf16 v[114:117], v[166:169], v[182:185], v[114:117]
	v_mfma_f32_16x16x32_bf16 v[106:109], v[174:177], v[182:185], v[106:109]
	v_mfma_f32_16x16x32_bf16 v[102:105], v[166:169], v[196:199], v[102:105]
	v_mfma_f32_16x16x32_bf16 v[94:97], v[174:177], v[196:199], v[94:97]
	v_mfma_f32_16x16x32_bf16 v[86:89], v[166:169], v[204:207], v[86:89]
	v_mfma_f32_16x16x32_bf16 v[78:81], v[174:177], v[204:207], v[78:81]
	v_mfma_f32_16x16x32_bf16 v[70:73], v[166:169], v[212:215], v[70:73]
	v_mfma_f32_16x16x32_bf16 v[66:69], v[174:177], v[212:215], v[66:69]
	s_barrier
	s_setprio 0
	ds_read_b128 v[178:181], v195 offset:16384
	ds_read_b128 v[182:185], v195 offset:17408
	ds_read_b128 v[186:189], v195 offset:18432
	ds_read_b128 v[196:199], v195 offset:19456
	ds_read_b128 v[200:203], v195 offset:20480
	ds_read_b128 v[204:207], v195 offset:21504
	ds_read_b128 v[208:211], v195 offset:22528
	ds_read_b128 v[212:215], v195 offset:23552
	v_lshl_add_u64 v[216:217], s[30:31], 0, v[148:149]
	s_add_i32 s69, s58, s44
	s_mov_b32 m0, s69
	s_nop 0
	global_load_lds_dwordx4 v[216:217], off
	s_add_i32 m0, s69, 0x2000
	v_lshl_add_u64 v[218:219], s[30:31], 0, v[152:153]
	global_load_lds_dwordx4 v[218:219], off
	s_add_u32 s70, s30, 0x100000
	s_addc_u32 s71, s31, 0
	v_lshl_add_u64 v[220:221], s[70:71], 0, v[148:149]
	s_add_i32 s69, s59, s44
	s_mov_b32 m0, s69
	s_nop 0
	global_load_lds_dwordx4 v[220:221], off
	v_lshl_add_u64 v[220:221], s[70:71], 0, v[152:153]
	s_add_i32 m0, s69, 0x2000
	s_nop 0
	global_load_lds_dwordx4 v[220:221], off
	v_lshl_add_u64 v[220:221], s[34:35], 0, v[146:147]
	s_mov_b32 m0, s45
	s_nop 0
	global_load_lds_dwordx4 v[220:221], off
	v_lshl_add_u64 v[222:223], s[34:35], 0, v[150:151]
	s_mov_b32 m0, s46
	s_nop 0
	global_load_lds_dwordx4 v[222:223], off
	s_setprio 1
	s_waitcnt vmcnt(8) lgkmcnt(0)
	s_barrier
	v_mfma_f32_16x16x32_bf16 v[62:65], v[130:133], v[178:181], v[62:65]
	v_mfma_f32_16x16x32_bf16 v[58:61], v[138:141], v[178:181], v[58:61]
	v_mfma_f32_16x16x32_bf16 v[46:49], v[130:133], v[186:189], v[46:49]
	v_mfma_f32_16x16x32_bf16 v[42:45], v[138:141], v[186:189], v[42:45]
	v_mfma_f32_16x16x32_bf16 v[30:33], v[130:133], v[200:203], v[30:33]
	v_mfma_f32_16x16x32_bf16 v[26:29], v[138:141], v[200:203], v[26:29]
	v_mfma_f32_16x16x32_bf16 v[14:17], v[130:133], v[208:211], v[14:17]
	v_mfma_f32_16x16x32_bf16 v[10:13], v[138:141], v[208:211], v[10:13]
	v_mfma_f32_16x16x32_bf16 v[62:65], v[134:137], v[182:185], v[62:65]
	v_mfma_f32_16x16x32_bf16 v[58:61], v[142:145], v[182:185], v[58:61]
	v_mfma_f32_16x16x32_bf16 v[46:49], v[134:137], v[196:199], v[46:49]
	v_mfma_f32_16x16x32_bf16 v[42:45], v[142:145], v[196:199], v[42:45]
	v_mfma_f32_16x16x32_bf16 v[30:33], v[134:137], v[204:207], v[30:33]
	v_mfma_f32_16x16x32_bf16 v[26:29], v[142:145], v[204:207], v[26:29]
	v_mfma_f32_16x16x32_bf16 v[14:17], v[134:137], v[212:215], v[14:17]
	v_mfma_f32_16x16x32_bf16 v[10:13], v[142:145], v[212:215], v[10:13]
	v_mfma_f32_16x16x32_bf16 v[54:57], v[162:165], v[178:181], v[54:57]
	v_mfma_f32_16x16x32_bf16 v[50:53], v[170:173], v[178:181], v[50:53]
	v_mfma_f32_16x16x32_bf16 v[38:41], v[162:165], v[186:189], v[38:41]
	v_mfma_f32_16x16x32_bf16 v[34:37], v[170:173], v[186:189], v[34:37]
	v_mfma_f32_16x16x32_bf16 v[22:25], v[162:165], v[200:203], v[22:25]
	v_mfma_f32_16x16x32_bf16 v[18:21], v[170:173], v[200:203], v[18:21]
	v_mfma_f32_16x16x32_bf16 v[6:9], v[162:165], v[208:211], v[6:9]
	v_mfma_f32_16x16x32_bf16 v[2:5], v[170:173], v[208:211], v[2:5]
	v_mfma_f32_16x16x32_bf16 v[54:57], v[166:169], v[182:185], v[54:57]
	v_mfma_f32_16x16x32_bf16 v[50:53], v[174:177], v[182:185], v[50:53]
	v_mfma_f32_16x16x32_bf16 v[38:41], v[166:169], v[196:199], v[38:41]
	v_mfma_f32_16x16x32_bf16 v[34:37], v[174:177], v[196:199], v[34:37]
	v_mfma_f32_16x16x32_bf16 v[22:25], v[166:169], v[204:207], v[22:25]
	v_mfma_f32_16x16x32_bf16 v[18:21], v[174:177], v[204:207], v[18:21]
	v_mfma_f32_16x16x32_bf16 v[6:9], v[166:169], v[212:215], v[6:9]
	v_mfma_f32_16x16x32_bf16 v[2:5], v[174:177], v[212:215], v[2:5]
	s_barrier
	s_setprio 0
	s_add_i32 s69, 0, 0x18000
	v_add_u32_e32 v142, s69, v192
	ds_read_b128 v[130:133], v142
	ds_read_b128 v[134:137], v142 offset:1024
	ds_read_b128 v[138:141], v142 offset:2048
	ds_read_b128 v[142:145], v142 offset:3072
	s_add_i32 s70, 0, 0x1c000
	v_add_u32_e32 v174, s70, v192
	ds_read_b128 v[162:165], v174
	ds_read_b128 v[166:169], v174 offset:1024
	ds_read_b128 v[170:173], v174 offset:2048
	ds_read_b128 v[174:177], v174 offset:3072
	ds_read_b128 v[178:181], v195 offset:32768
	ds_read_b128 v[182:185], v195 offset:33792
	ds_read_b128 v[186:189], v195 offset:34816
	ds_read_b128 v[196:199], v195 offset:35840
	ds_read_b128 v[200:203], v195 offset:36864
	ds_read_b128 v[204:207], v195 offset:37888
	ds_read_b128 v[208:211], v195 offset:38912
	ds_read_b128 v[212:215], v195 offset:39936
	s_mov_b32 m0, s47
	s_add_u32 s34, s34, 0x100000
	s_addc_u32 s35, s35, 0
	v_lshl_add_u64 v[224:225], s[34:35], 0, v[146:147]
	global_load_lds_dwordx4 v[224:225], off
	v_lshl_add_u64 v[224:225], s[34:35], 0, v[150:151]
	s_mov_b32 m0, s48
	s_nop 0
	global_load_lds_dwordx4 v[224:225], off
	s_setprio 1
	s_waitcnt vmcnt(8) lgkmcnt(0)
	s_barrier
	v_mfma_f32_16x16x32_bf16 v[126:129], v[130:133], v[178:181], v[126:129]
	v_mfma_f32_16x16x32_bf16 v[122:125], v[138:141], v[178:181], v[122:125]
	v_mfma_f32_16x16x32_bf16 v[118:121], v[130:133], v[186:189], v[118:121]
	v_mfma_f32_16x16x32_bf16 v[110:113], v[138:141], v[186:189], v[110:113]
	v_mfma_f32_16x16x32_bf16 v[98:101], v[130:133], v[200:203], v[98:101]
	v_mfma_f32_16x16x32_bf16 v[90:93], v[138:141], v[200:203], v[90:93]
	v_mfma_f32_16x16x32_bf16 v[82:85], v[130:133], v[208:211], v[82:85]
	v_mfma_f32_16x16x32_bf16 v[74:77], v[138:141], v[208:211], v[74:77]
	v_mfma_f32_16x16x32_bf16 v[126:129], v[134:137], v[182:185], v[126:129]
	v_mfma_f32_16x16x32_bf16 v[122:125], v[142:145], v[182:185], v[122:125]
	v_mfma_f32_16x16x32_bf16 v[118:121], v[134:137], v[196:199], v[118:121]
	v_mfma_f32_16x16x32_bf16 v[110:113], v[142:145], v[196:199], v[110:113]
	v_mfma_f32_16x16x32_bf16 v[98:101], v[134:137], v[204:207], v[98:101]
	v_mfma_f32_16x16x32_bf16 v[90:93], v[142:145], v[204:207], v[90:93]
	v_mfma_f32_16x16x32_bf16 v[82:85], v[134:137], v[212:215], v[82:85]
	v_mfma_f32_16x16x32_bf16 v[74:77], v[142:145], v[212:215], v[74:77]
	v_mfma_f32_16x16x32_bf16 v[114:117], v[162:165], v[178:181], v[114:117]
	v_mfma_f32_16x16x32_bf16 v[106:109], v[170:173], v[178:181], v[106:109]
	v_mfma_f32_16x16x32_bf16 v[102:105], v[162:165], v[186:189], v[102:105]
	v_mfma_f32_16x16x32_bf16 v[94:97], v[170:173], v[186:189], v[94:97]
	v_mfma_f32_16x16x32_bf16 v[86:89], v[162:165], v[200:203], v[86:89]
	v_mfma_f32_16x16x32_bf16 v[78:81], v[170:173], v[200:203], v[78:81]
	v_mfma_f32_16x16x32_bf16 v[70:73], v[162:165], v[208:211], v[70:73]
	v_mfma_f32_16x16x32_bf16 v[66:69], v[170:173], v[208:211], v[66:69]
	v_mfma_f32_16x16x32_bf16 v[114:117], v[166:169], v[182:185], v[114:117]
	v_mfma_f32_16x16x32_bf16 v[106:109], v[174:177], v[182:185], v[106:109]
	v_mfma_f32_16x16x32_bf16 v[102:105], v[166:169], v[196:199], v[102:105]
	v_mfma_f32_16x16x32_bf16 v[94:97], v[174:177], v[196:199], v[94:97]
	v_mfma_f32_16x16x32_bf16 v[86:89], v[166:169], v[204:207], v[86:89]
	v_mfma_f32_16x16x32_bf16 v[78:81], v[174:177], v[204:207], v[78:81]
	v_mfma_f32_16x16x32_bf16 v[70:73], v[166:169], v[212:215], v[70:73]
	v_mfma_f32_16x16x32_bf16 v[66:69], v[174:177], v[212:215], v[66:69]
	s_barrier
	s_setprio 0
	ds_read_b128 v[178:181], v195 offset:49152
	ds_read_b128 v[182:185], v195 offset:50176
	ds_read_b128 v[186:189], v195 offset:51200
	ds_read_b128 v[196:199], v195 offset:52224
	ds_read_b128 v[200:203], v195 offset:53248
	ds_read_b128 v[204:207], v195 offset:54272
	ds_read_b128 v[208:211], v195 offset:55296
	ds_read_b128 v[212:215], v195 offset:56320
	v_lshl_add_u64 v[216:217], v[216:217], 0, s[12:13]
	s_add_i32 s34, s69, s44
	s_mov_b32 m0, s34
	s_nop 0
	global_load_lds_dwordx4 v[216:217], off
	s_add_i32 m0, s34, 0x2000
	v_lshl_add_u64 v[216:217], v[218:219], 0, s[12:13]
	global_load_lds_dwordx4 v[216:217], off
	s_add_u32 s30, s30, 0x100080
	s_addc_u32 s31, s31, 0
	v_lshl_add_u64 v[216:217], s[30:31], 0, v[148:149]
	s_add_i32 s34, s70, s44
	s_mov_b32 m0, s34
	s_nop 0
	global_load_lds_dwordx4 v[216:217], off
	v_lshl_add_u64 v[216:217], s[30:31], 0, v[152:153]
	s_add_i32 m0, s34, 0x2000
	s_nop 0
	global_load_lds_dwordx4 v[216:217], off
	v_lshl_add_u64 v[216:217], v[220:221], 0, s[12:13]
	s_mov_b32 m0, s55
	s_nop 0
	global_load_lds_dwordx4 v[216:217], off
	v_lshl_add_u64 v[216:217], v[222:223], 0, s[12:13]
	s_mov_b32 m0, s56
	s_nop 0
	global_load_lds_dwordx4 v[216:217], off
	s_setprio 1
	s_waitcnt vmcnt(8) lgkmcnt(0)
	s_barrier
	v_mfma_f32_16x16x32_bf16 v[62:65], v[130:133], v[178:181], v[62:65]
	v_mfma_f32_16x16x32_bf16 v[58:61], v[138:141], v[178:181], v[58:61]
	v_mfma_f32_16x16x32_bf16 v[46:49], v[130:133], v[186:189], v[46:49]
	v_mfma_f32_16x16x32_bf16 v[42:45], v[138:141], v[186:189], v[42:45]
	v_mfma_f32_16x16x32_bf16 v[30:33], v[130:133], v[200:203], v[30:33]
	v_mfma_f32_16x16x32_bf16 v[26:29], v[138:141], v[200:203], v[26:29]
	v_mfma_f32_16x16x32_bf16 v[14:17], v[130:133], v[208:211], v[14:17]
	v_mfma_f32_16x16x32_bf16 v[10:13], v[138:141], v[208:211], v[10:13]
	v_mfma_f32_16x16x32_bf16 v[62:65], v[134:137], v[182:185], v[62:65]
	v_mfma_f32_16x16x32_bf16 v[58:61], v[142:145], v[182:185], v[58:61]
	v_mfma_f32_16x16x32_bf16 v[46:49], v[134:137], v[196:199], v[46:49]
	v_mfma_f32_16x16x32_bf16 v[42:45], v[142:145], v[196:199], v[42:45]
	v_mfma_f32_16x16x32_bf16 v[30:33], v[134:137], v[204:207], v[30:33]
	v_mfma_f32_16x16x32_bf16 v[26:29], v[142:145], v[204:207], v[26:29]
	v_mfma_f32_16x16x32_bf16 v[14:17], v[134:137], v[212:215], v[14:17]
	v_mfma_f32_16x16x32_bf16 v[10:13], v[142:145], v[212:215], v[10:13]
	v_mfma_f32_16x16x32_bf16 v[54:57], v[162:165], v[178:181], v[54:57]
	v_mfma_f32_16x16x32_bf16 v[50:53], v[170:173], v[178:181], v[50:53]
	v_mfma_f32_16x16x32_bf16 v[38:41], v[162:165], v[186:189], v[38:41]
	v_mfma_f32_16x16x32_bf16 v[34:37], v[170:173], v[186:189], v[34:37]
	v_mfma_f32_16x16x32_bf16 v[22:25], v[162:165], v[200:203], v[22:25]
	v_mfma_f32_16x16x32_bf16 v[18:21], v[170:173], v[200:203], v[18:21]
	v_mfma_f32_16x16x32_bf16 v[6:9], v[162:165], v[208:211], v[6:9]
	v_mfma_f32_16x16x32_bf16 v[2:5], v[170:173], v[208:211], v[2:5]
	v_mfma_f32_16x16x32_bf16 v[54:57], v[166:169], v[182:185], v[54:57]
	v_mfma_f32_16x16x32_bf16 v[50:53], v[174:177], v[182:185], v[50:53]
	v_mfma_f32_16x16x32_bf16 v[38:41], v[166:169], v[196:199], v[38:41]
	v_mfma_f32_16x16x32_bf16 v[34:37], v[174:177], v[196:199], v[34:37]
	v_mfma_f32_16x16x32_bf16 v[22:25], v[166:169], v[204:207], v[22:25]
	v_mfma_f32_16x16x32_bf16 v[18:21], v[174:177], v[204:207], v[18:21]
	v_mfma_f32_16x16x32_bf16 v[6:9], v[166:169], v[212:215], v[6:9]
	v_mfma_f32_16x16x32_bf16 v[2:5], v[174:177], v[212:215], v[2:5]
	s_barrier
	s_setprio 0
	s_add_i32 s68, s68, 2
	s_add_u32 s28, s28, 0x100
	s_addc_u32 s29, s29, 0
	s_add_u32 s63, s63, 0x100
	s_addc_u32 s65, s65, 0
	s_cmp_gt_u32 s68, 61
	s_cbranch_scc0 .LBB0_1246
	s_and_b64 vcc, exec, s[14:15]
	s_cbranch_vccz .LBB0_1249
	s_barrier

.LBB0_1521:
	ds_read_b128 v[130:133], v169
	ds_read_b128 v[134:137], v169 offset:1024
	ds_read_b128 v[138:141], v169 offset:2048
	ds_read_b128 v[142:145], v169 offset:3072
	ds_read_b128 v[162:165], v170
	ds_read_b128 v[172:175], v170 offset:1024
	ds_read_b128 v[176:179], v170 offset:2048
	ds_read_b128 v[180:183], v170 offset:3072
	ds_read_b128 v[184:187], v171
	ds_read_b128 v[188:191], v171 offset:1024
	ds_read_b128 v[192:195], v171 offset:2048
	ds_read_b128 v[196:199], v171 offset:3072
	ds_read_b128 v[200:203], v171 offset:4096
	ds_read_b128 v[204:207], v171 offset:5120
	ds_read_b128 v[208:211], v171 offset:6144
	ds_read_b128 v[212:215], v171 offset:7168
	v_lshl_add_u64 v[216:217], s[2:3], 0, v[154:155]
	s_add_i32 m0, s37, 0xc000
	s_nop 0
	global_load_lds_dwordx4 v[216:217], off
	v_lshl_add_u64 v[216:217], s[2:3], 0, v[156:157]
	s_add_i32 m0, s37, 0xe000
	s_nop 0
	global_load_lds_dwordx4 v[216:217], off
	s_add_u32 s38, s2, 0xfff00080
	s_addc_u32 s39, s3, -1
	s_cmp_eq_u32 s69, 60
	s_cselect_b32 s45, s29, s39
	s_cselect_b32 s44, s65, s38
	s_cselect_b32 s39, s27, s68
	s_cselect_b32 s38, s66, s67
	s_setprio 1
	s_waitcnt vmcnt(8) lgkmcnt(0)
	s_barrier
	v_mfma_f32_16x16x32_bf16 v[126:129], v[130:133], v[184:187], v[126:129]
	v_mfma_f32_16x16x32_bf16 v[122:125], v[138:141], v[184:187], v[122:125]
	v_mfma_f32_16x16x32_bf16 v[114:117], v[130:133], v[192:195], v[114:117]
	v_mfma_f32_16x16x32_bf16 v[106:109], v[138:141], v[192:195], v[106:109]
	v_mfma_f32_16x16x32_bf16 v[98:101], v[130:133], v[200:203], v[98:101]
	v_mfma_f32_16x16x32_bf16 v[90:93], v[138:141], v[200:203], v[90:93]
	v_mfma_f32_16x16x32_bf16 v[82:85], v[130:133], v[208:211], v[82:85]
	v_mfma_f32_16x16x32_bf16 v[74:77], v[138:141], v[208:211], v[74:77]
	v_mfma_f32_16x16x32_bf16 v[126:129], v[134:137], v[188:191], v[126:129]
	v_mfma_f32_16x16x32_bf16 v[122:125], v[142:145], v[188:191], v[122:125]
	v_mfma_f32_16x16x32_bf16 v[114:117], v[134:137], v[196:199], v[114:117]
	v_mfma_f32_16x16x32_bf16 v[106:109], v[142:145], v[196:199], v[106:109]
	v_mfma_f32_16x16x32_bf16 v[98:101], v[134:137], v[204:207], v[98:101]
	v_mfma_f32_16x16x32_bf16 v[90:93], v[142:145], v[204:207], v[90:93]
	v_mfma_f32_16x16x32_bf16 v[82:85], v[134:137], v[212:215], v[82:85]
	v_mfma_f32_16x16x32_bf16 v[74:77], v[142:145], v[212:215], v[74:77]
	v_mfma_f32_16x16x32_bf16 v[118:121], v[162:165], v[184:187], v[118:121]
	v_mfma_f32_16x16x32_bf16 v[110:113], v[176:179], v[184:187], v[110:113]
	v_mfma_f32_16x16x32_bf16 v[102:105], v[162:165], v[192:195], v[102:105]
	v_mfma_f32_16x16x32_bf16 v[94:97], v[176:179], v[192:195], v[94:97]
	v_mfma_f32_16x16x32_bf16 v[86:89], v[162:165], v[200:203], v[86:89]
	v_mfma_f32_16x16x32_bf16 v[78:81], v[176:179], v[200:203], v[78:81]
	v_mfma_f32_16x16x32_bf16 v[70:73], v[162:165], v[208:211], v[70:73]
	v_mfma_f32_16x16x32_bf16 v[66:69], v[176:179], v[208:211], v[66:69]
	v_mfma_f32_16x16x32_bf16 v[118:121], v[172:175], v[188:191], v[118:121]
	v_mfma_f32_16x16x32_bf16 v[110:113], v[180:183], v[188:191], v[110:113]
	v_mfma_f32_16x16x32_bf16 v[102:105], v[172:175], v[196:199], v[102:105]
	v_mfma_f32_16x16x32_bf16 v[94:97], v[180:183], v[196:199], v[94:97]
	v_mfma_f32_16x16x32_bf16 v[86:89], v[172:175], v[204:207], v[86:89]
	v_mfma_f32_16x16x32_bf16 v[78:81], v[180:183], v[204:207], v[78:81]
	v_mfma_f32_16x16x32_bf16 v[70:73], v[172:175], v[212:215], v[70:73]
	v_mfma_f32_16x16x32_bf16 v[66:69], v[180:183], v[212:215], v[66:69]
	s_barrier
	s_setprio 0
	ds_read_b128 v[184:187], v171 offset:16384
	ds_read_b128 v[188:191], v171 offset:17408
	ds_read_b128 v[192:195], v171 offset:18432
	ds_read_b128 v[196:199], v171 offset:19456
	ds_read_b128 v[200:203], v171 offset:20480
	ds_read_b128 v[204:207], v171 offset:21504
	ds_read_b128 v[208:211], v171 offset:22528
	ds_read_b128 v[212:215], v171 offset:23552
	v_lshl_add_u64 v[216:217], s[38:39], 0, v[150:151]
	s_add_i32 s43, s57, s50
	s_mov_b32 m0, s43
	s_nop 0
	global_load_lds_dwordx4 v[216:217], off
	s_add_i32 m0, s43, 0x2000
	v_lshl_add_u64 v[218:219], s[38:39], 0, v[146:147]
	global_load_lds_dwordx4 v[218:219], off
	s_add_u32 s70, s38, 0x100000
	s_addc_u32 s71, s39, 0
	v_lshl_add_u64 v[220:221], s[70:71], 0, v[150:151]
	s_add_i32 s43, s58, s50
	s_mov_b32 m0, s43
	s_nop 0
	global_load_lds_dwordx4 v[220:221], off
	v_lshl_add_u64 v[220:221], s[70:71], 0, v[146:147]
	s_add_i32 m0, s43, 0x2000
	s_nop 0
	global_load_lds_dwordx4 v[220:221], off
	v_lshl_add_u64 v[220:221], s[44:45], 0, v[152:153]
	s_mov_b32 m0, s37
	s_nop 0
	global_load_lds_dwordx4 v[220:221], off
	v_lshl_add_u64 v[222:223], s[44:45], 0, v[148:149]
	s_mov_b32 m0, s51
	s_nop 0
	global_load_lds_dwordx4 v[222:223], off
	s_setprio 1
	s_waitcnt vmcnt(8) lgkmcnt(0)
	s_barrier
	v_mfma_f32_16x16x32_bf16 v[62:65], v[130:133], v[184:187], v[62:65]
	v_mfma_f32_16x16x32_bf16 v[58:61], v[138:141], v[184:187], v[58:61]
	v_mfma_f32_16x16x32_bf16 v[50:53], v[130:133], v[192:195], v[50:53]
	v_mfma_f32_16x16x32_bf16 v[42:45], v[138:141], v[192:195], v[42:45]
	v_mfma_f32_16x16x32_bf16 v[34:37], v[130:133], v[200:203], v[34:37]
	v_mfma_f32_16x16x32_bf16 v[26:29], v[138:141], v[200:203], v[26:29]
	v_mfma_f32_16x16x32_bf16 v[18:21], v[130:133], v[208:211], v[18:21]
	v_mfma_f32_16x16x32_bf16 v[10:13], v[138:141], v[208:211], v[10:13]
	v_mfma_f32_16x16x32_bf16 v[62:65], v[134:137], v[188:191], v[62:65]
	v_mfma_f32_16x16x32_bf16 v[58:61], v[142:145], v[188:191], v[58:61]
	v_mfma_f32_16x16x32_bf16 v[50:53], v[134:137], v[196:199], v[50:53]
	v_mfma_f32_16x16x32_bf16 v[42:45], v[142:145], v[196:199], v[42:45]
	v_mfma_f32_16x16x32_bf16 v[34:37], v[134:137], v[204:207], v[34:37]
	v_mfma_f32_16x16x32_bf16 v[26:29], v[142:145], v[204:207], v[26:29]
	v_mfma_f32_16x16x32_bf16 v[18:21], v[134:137], v[212:215], v[18:21]
	v_mfma_f32_16x16x32_bf16 v[10:13], v[142:145], v[212:215], v[10:13]
	v_mfma_f32_16x16x32_bf16 v[54:57], v[162:165], v[184:187], v[54:57]
	v_mfma_f32_16x16x32_bf16 v[46:49], v[176:179], v[184:187], v[46:49]
	v_mfma_f32_16x16x32_bf16 v[38:41], v[162:165], v[192:195], v[38:41]
	v_mfma_f32_16x16x32_bf16 v[30:33], v[176:179], v[192:195], v[30:33]
	v_mfma_f32_16x16x32_bf16 v[22:25], v[162:165], v[200:203], v[22:25]
	v_mfma_f32_16x16x32_bf16 v[14:17], v[176:179], v[200:203], v[14:17]
	v_mfma_f32_16x16x32_bf16 v[6:9], v[162:165], v[208:211], v[6:9]
	v_mfma_f32_16x16x32_bf16 v[2:5], v[176:179], v[208:211], v[2:5]
	v_mfma_f32_16x16x32_bf16 v[54:57], v[172:175], v[188:191], v[54:57]
	v_mfma_f32_16x16x32_bf16 v[46:49], v[180:183], v[188:191], v[46:49]
	v_mfma_f32_16x16x32_bf16 v[38:41], v[172:175], v[196:199], v[38:41]
	v_mfma_f32_16x16x32_bf16 v[30:33], v[180:183], v[196:199], v[30:33]
	v_mfma_f32_16x16x32_bf16 v[22:25], v[172:175], v[204:207], v[22:25]
	v_mfma_f32_16x16x32_bf16 v[14:17], v[180:183], v[204:207], v[14:17]
	v_mfma_f32_16x16x32_bf16 v[6:9], v[172:175], v[212:215], v[6:9]
	v_mfma_f32_16x16x32_bf16 v[2:5], v[180:183], v[212:215], v[2:5]
	s_barrier
	s_setprio 0
	s_add_i32 s43, 0, 0x18000
	v_add_u32_e32 v142, s43, v167
	ds_read_b128 v[130:133], v142
	ds_read_b128 v[134:137], v142 offset:1024
	ds_read_b128 v[138:141], v142 offset:2048
	ds_read_b128 v[142:145], v142 offset:3072
	s_add_i32 s70, 0, 0x1c000
	v_add_u32_e32 v180, s70, v167
	ds_read_b128 v[162:165], v180
	ds_read_b128 v[172:175], v180 offset:1024
	ds_read_b128 v[176:179], v180 offset:2048
	ds_read_b128 v[180:183], v180 offset:3072
	ds_read_b128 v[184:187], v171 offset:32768
	ds_read_b128 v[188:191], v171 offset:33792
	ds_read_b128 v[192:195], v171 offset:34816
	ds_read_b128 v[196:199], v171 offset:35840
	ds_read_b128 v[200:203], v171 offset:36864
	ds_read_b128 v[204:207], v171 offset:37888
	ds_read_b128 v[208:211], v171 offset:38912
	ds_read_b128 v[212:215], v171 offset:39936
	s_mov_b32 m0, s52
	s_add_u32 s44, s44, 0x100000
	s_addc_u32 s45, s45, 0
	v_lshl_add_u64 v[224:225], s[44:45], 0, v[152:153]
	global_load_lds_dwordx4 v[224:225], off
	v_lshl_add_u64 v[224:225], s[44:45], 0, v[148:149]
	s_mov_b32 m0, s53
	s_nop 0
	global_load_lds_dwordx4 v[224:225], off
	s_setprio 1
	s_waitcnt vmcnt(8) lgkmcnt(0)
	s_barrier
	v_mfma_f32_16x16x32_bf16 v[126:129], v[130:133], v[184:187], v[126:129]
	v_mfma_f32_16x16x32_bf16 v[122:125], v[138:141], v[184:187], v[122:125]
	v_mfma_f32_16x16x32_bf16 v[114:117], v[130:133], v[192:195], v[114:117]
	v_mfma_f32_16x16x32_bf16 v[106:109], v[138:141], v[192:195], v[106:109]
	v_mfma_f32_16x16x32_bf16 v[98:101], v[130:133], v[200:203], v[98:101]
	v_mfma_f32_16x16x32_bf16 v[90:93], v[138:141], v[200:203], v[90:93]
	v_mfma_f32_16x16x32_bf16 v[82:85], v[130:133], v[208:211], v[82:85]
	v_mfma_f32_16x16x32_bf16 v[74:77], v[138:141], v[208:211], v[74:77]
	v_mfma_f32_16x16x32_bf16 v[126:129], v[134:137], v[188:191], v[126:129]
	v_mfma_f32_16x16x32_bf16 v[122:125], v[142:145], v[188:191], v[122:125]
	v_mfma_f32_16x16x32_bf16 v[114:117], v[134:137], v[196:199], v[114:117]
	v_mfma_f32_16x16x32_bf16 v[106:109], v[142:145], v[196:199], v[106:109]
	v_mfma_f32_16x16x32_bf16 v[98:101], v[134:137], v[204:207], v[98:101]
	v_mfma_f32_16x16x32_bf16 v[90:93], v[142:145], v[204:207], v[90:93]
	v_mfma_f32_16x16x32_bf16 v[82:85], v[134:137], v[212:215], v[82:85]
	v_mfma_f32_16x16x32_bf16 v[74:77], v[142:145], v[212:215], v[74:77]
	v_mfma_f32_16x16x32_bf16 v[118:121], v[162:165], v[184:187], v[118:121]
	v_mfma_f32_16x16x32_bf16 v[110:113], v[176:179], v[184:187], v[110:113]
	v_mfma_f32_16x16x32_bf16 v[102:105], v[162:165], v[192:195], v[102:105]
	v_mfma_f32_16x16x32_bf16 v[94:97], v[176:179], v[192:195], v[94:97]
	v_mfma_f32_16x16x32_bf16 v[86:89], v[162:165], v[200:203], v[86:89]
	v_mfma_f32_16x16x32_bf16 v[78:81], v[176:179], v[200:203], v[78:81]
	v_mfma_f32_16x16x32_bf16 v[70:73], v[162:165], v[208:211], v[70:73]
	v_mfma_f32_16x16x32_bf16 v[66:69], v[176:179], v[208:211], v[66:69]
	v_mfma_f32_16x16x32_bf16 v[118:121], v[172:175], v[188:191], v[118:121]
	v_mfma_f32_16x16x32_bf16 v[110:113], v[180:183], v[188:191], v[110:113]
	v_mfma_f32_16x16x32_bf16 v[102:105], v[172:175], v[196:199], v[102:105]
	v_mfma_f32_16x16x32_bf16 v[94:97], v[180:183], v[196:199], v[94:97]
	v_mfma_f32_16x16x32_bf16 v[86:89], v[172:175], v[204:207], v[86:89]
	v_mfma_f32_16x16x32_bf16 v[78:81], v[180:183], v[204:207], v[78:81]
	v_mfma_f32_16x16x32_bf16 v[70:73], v[172:175], v[212:215], v[70:73]
	v_mfma_f32_16x16x32_bf16 v[66:69], v[180:183], v[212:215], v[66:69]
	s_barrier
	s_setprio 0
	ds_read_b128 v[184:187], v171 offset:49152
	ds_read_b128 v[188:191], v171 offset:50176
	ds_read_b128 v[192:195], v171 offset:51200
	ds_read_b128 v[196:199], v171 offset:52224
	ds_read_b128 v[200:203], v171 offset:53248
	ds_read_b128 v[204:207], v171 offset:54272
	ds_read_b128 v[208:211], v171 offset:55296
	ds_read_b128 v[212:215], v171 offset:56320
	v_lshl_add_u64 v[216:217], v[216:217], 0, s[16:17]
	s_add_i32 s43, s43, s50
	s_mov_b32 m0, s43
	s_nop 0
	global_load_lds_dwordx4 v[216:217], off
	s_add_i32 m0, s43, 0x2000
	v_lshl_add_u64 v[216:217], v[218:219], 0, s[16:17]
	global_load_lds_dwordx4 v[216:217], off
	s_add_u32 s38, s38, 0x100080
	s_addc_u32 s39, s39, 0
	v_lshl_add_u64 v[216:217], s[38:39], 0, v[150:151]
	s_add_i32 s43, s70, s50
	s_mov_b32 m0, s43
	s_nop 0
	global_load_lds_dwordx4 v[216:217], off
	v_lshl_add_u64 v[216:217], s[38:39], 0, v[146:147]
	s_add_i32 m0, s43, 0x2000
	s_nop 0
	global_load_lds_dwordx4 v[216:217], off
	v_lshl_add_u64 v[216:217], v[220:221], 0, s[16:17]
	s_mov_b32 m0, s55
	s_nop 0
	global_load_lds_dwordx4 v[216:217], off
	v_lshl_add_u64 v[216:217], v[222:223], 0, s[16:17]
	s_mov_b32 m0, s56
	s_nop 0
	global_load_lds_dwordx4 v[216:217], off
	s_setprio 1
	s_waitcnt vmcnt(8) lgkmcnt(0)
	s_barrier
	v_mfma_f32_16x16x32_bf16 v[62:65], v[130:133], v[184:187], v[62:65]
	v_mfma_f32_16x16x32_bf16 v[58:61], v[138:141], v[184:187], v[58:61]
	v_mfma_f32_16x16x32_bf16 v[50:53], v[130:133], v[192:195], v[50:53]
	v_mfma_f32_16x16x32_bf16 v[42:45], v[138:141], v[192:195], v[42:45]
	v_mfma_f32_16x16x32_bf16 v[34:37], v[130:133], v[200:203], v[34:37]
	v_mfma_f32_16x16x32_bf16 v[26:29], v[138:141], v[200:203], v[26:29]
	v_mfma_f32_16x16x32_bf16 v[18:21], v[130:133], v[208:211], v[18:21]
	v_mfma_f32_16x16x32_bf16 v[10:13], v[138:141], v[208:211], v[10:13]
	v_mfma_f32_16x16x32_bf16 v[62:65], v[134:137], v[188:191], v[62:65]
	v_mfma_f32_16x16x32_bf16 v[58:61], v[142:145], v[188:191], v[58:61]
	v_mfma_f32_16x16x32_bf16 v[50:53], v[134:137], v[196:199], v[50:53]
	v_mfma_f32_16x16x32_bf16 v[42:45], v[142:145], v[196:199], v[42:45]
	v_mfma_f32_16x16x32_bf16 v[34:37], v[134:137], v[204:207], v[34:37]
	v_mfma_f32_16x16x32_bf16 v[26:29], v[142:145], v[204:207], v[26:29]
	v_mfma_f32_16x16x32_bf16 v[18:21], v[134:137], v[212:215], v[18:21]
	v_mfma_f32_16x16x32_bf16 v[10:13], v[142:145], v[212:215], v[10:13]
	v_mfma_f32_16x16x32_bf16 v[54:57], v[162:165], v[184:187], v[54:57]
	v_mfma_f32_16x16x32_bf16 v[46:49], v[176:179], v[184:187], v[46:49]
	v_mfma_f32_16x16x32_bf16 v[38:41], v[162:165], v[192:195], v[38:41]
	v_mfma_f32_16x16x32_bf16 v[30:33], v[176:179], v[192:195], v[30:33]
	v_mfma_f32_16x16x32_bf16 v[22:25], v[162:165], v[200:203], v[22:25]
	v_mfma_f32_16x16x32_bf16 v[14:17], v[176:179], v[200:203], v[14:17]
	v_mfma_f32_16x16x32_bf16 v[6:9], v[162:165], v[208:211], v[6:9]
	v_mfma_f32_16x16x32_bf16 v[2:5], v[176:179], v[208:211], v[2:5]
	v_mfma_f32_16x16x32_bf16 v[54:57], v[172:175], v[188:191], v[54:57]
	v_mfma_f32_16x16x32_bf16 v[46:49], v[180:183], v[188:191], v[46:49]
	v_mfma_f32_16x16x32_bf16 v[38:41], v[172:175], v[196:199], v[38:41]
	v_mfma_f32_16x16x32_bf16 v[30:33], v[180:183], v[196:199], v[30:33]
	v_mfma_f32_16x16x32_bf16 v[22:25], v[172:175], v[204:207], v[22:25]
	v_mfma_f32_16x16x32_bf16 v[14:17], v[180:183], v[204:207], v[14:17]
	v_mfma_f32_16x16x32_bf16 v[6:9], v[172:175], v[212:215], v[6:9]
	v_mfma_f32_16x16x32_bf16 v[2:5], v[180:183], v[212:215], v[2:5]
	s_barrier
	s_setprio 0
	s_add_i32 s69, s69, 2
	s_add_u32 s2, s2, 0x100
	s_addc_u32 s3, s3, 0
	s_add_u32 s67, s67, 0x100
	s_addc_u32 s68, s68, 0
	s_cmp_gt_u32 s69, 61
	s_cbranch_scc0 .LBB0_1521
	s_and_b64 vcc, exec, s[18:19]
	s_cbranch_vccz .LBB0_1524
	s_barrier

.LBB0_1697:
	ds_read_b128 v[130:133], v238
	ds_read_b128 v[134:137], v238 offset:1024
	ds_read_b128 v[138:141], v238 offset:2048
	ds_read_b128 v[142:145], v238 offset:3072
	ds_read_b128 v[146:149], v239
	ds_read_b128 v[150:153], v239 offset:1024
	ds_read_b128 v[154:157], v239 offset:2048
	ds_read_b128 v[158:161], v239 offset:3072
	ds_read_b128 v[162:165], v240
	ds_read_b128 v[166:169], v240 offset:1024
	ds_read_b128 v[170:173], v240 offset:2048
	ds_read_b128 v[174:177], v240 offset:3072
	ds_read_b128 v[178:181], v240 offset:4096
	ds_read_b128 v[182:185], v240 offset:5120
	ds_read_b128 v[186:189], v240 offset:6144
	ds_read_b128 v[190:193], v240 offset:7168
	v_lshl_add_u64 v[194:195], s[2:3], 0, v[210:211]
	s_add_i32 m0, s55, 0xc000
	s_nop 0
	global_load_lds_dwordx4 v[194:195], off
	v_lshl_add_u64 v[194:195], s[2:3], 0, v[212:213]
	s_add_i32 m0, s55, 0xe000
	s_nop 0
	global_load_lds_dwordx4 v[194:195], off
	s_add_u32 s56, s2, 0x100
	s_addc_u32 s57, s3, 0
	s_cmp_eq_u32 s91, 28
	s_cselect_b32 s61, s49, s57
	s_cselect_b32 s60, s87, s56
	s_cselect_b32 s59, s47, s90
	s_cselect_b32 s58, s88, s89
	s_setprio 1
	s_waitcnt vmcnt(8) lgkmcnt(0)
	s_barrier
	v_mfma_i32_16x16x64_i8 v[126:129], v[130:133], v[162:165], v[126:129]
	v_mfma_i32_16x16x64_i8 v[122:125], v[138:141], v[162:165], v[122:125]
	v_mfma_i32_16x16x64_i8 v[118:121], v[130:133], v[170:173], v[118:121]
	v_mfma_i32_16x16x64_i8 v[110:113], v[138:141], v[170:173], v[110:113]
	v_mfma_i32_16x16x64_i8 v[78:81], v[130:133], v[178:181], v[78:81]
	v_mfma_i32_16x16x64_i8 v[30:33], v[138:141], v[178:181], v[30:33]
	v_mfma_i32_16x16x64_i8 v[74:77], v[130:133], v[186:189], v[74:77]
	v_mfma_i32_16x16x64_i8 v[26:29], v[138:141], v[186:189], v[26:29]
	v_mfma_i32_16x16x64_i8 v[126:129], v[134:137], v[166:169], v[126:129]
	v_mfma_i32_16x16x64_i8 v[122:125], v[142:145], v[166:169], v[122:125]
	v_mfma_i32_16x16x64_i8 v[118:121], v[134:137], v[174:177], v[118:121]
	v_mfma_i32_16x16x64_i8 v[110:113], v[142:145], v[174:177], v[110:113]
	v_mfma_i32_16x16x64_i8 v[78:81], v[134:137], v[182:185], v[78:81]
	v_mfma_i32_16x16x64_i8 v[30:33], v[142:145], v[182:185], v[30:33]
	v_mfma_i32_16x16x64_i8 v[74:77], v[134:137], v[190:193], v[74:77]
	v_mfma_i32_16x16x64_i8 v[26:29], v[142:145], v[190:193], v[26:29]
	v_mfma_i32_16x16x64_i8 v[102:105], v[146:149], v[162:165], v[102:105]
	v_mfma_i32_16x16x64_i8 v[98:101], v[154:157], v[162:165], v[98:101]
	v_mfma_i32_16x16x64_i8 v[94:97], v[146:149], v[170:173], v[94:97]
	v_mfma_i32_16x16x64_i8 v[90:93], v[154:157], v[170:173], v[90:93]
	v_mfma_i32_16x16x64_i8 v[70:73], v[146:149], v[178:181], v[70:73]
	v_mfma_i32_16x16x64_i8 v[22:25], v[154:157], v[178:181], v[22:25]
	v_mfma_i32_16x16x64_i8 v[66:69], v[146:149], v[186:189], v[66:69]
	v_mfma_i32_16x16x64_i8 v[18:21], v[154:157], v[186:189], v[18:21]
	v_mfma_i32_16x16x64_i8 v[102:105], v[150:153], v[166:169], v[102:105]
	v_mfma_i32_16x16x64_i8 v[98:101], v[158:161], v[166:169], v[98:101]
	v_mfma_i32_16x16x64_i8 v[94:97], v[150:153], v[174:177], v[94:97]
	v_mfma_i32_16x16x64_i8 v[90:93], v[158:161], v[174:177], v[90:93]
	v_mfma_i32_16x16x64_i8 v[70:73], v[150:153], v[182:185], v[70:73]
	v_mfma_i32_16x16x64_i8 v[22:25], v[158:161], v[182:185], v[22:25]
	v_mfma_i32_16x16x64_i8 v[66:69], v[150:153], v[190:193], v[66:69]
	v_mfma_i32_16x16x64_i8 v[18:21], v[158:161], v[190:193], v[18:21]
	s_barrier
	s_setprio 0
	ds_read_b128 v[162:165], v240 offset:16384
	ds_read_b128 v[166:169], v240 offset:17408
	ds_read_b128 v[170:173], v240 offset:18432
	ds_read_b128 v[174:177], v240 offset:19456
	ds_read_b128 v[178:181], v240 offset:20480
	ds_read_b128 v[182:185], v240 offset:21504
	ds_read_b128 v[186:189], v240 offset:22528
	ds_read_b128 v[190:193], v240 offset:23552
	v_lshl_add_u64 v[194:195], s[58:59], 0, v[206:207]
	s_add_i32 s2, s83, s66
	s_mov_b32 m0, s2
	s_nop 0
	global_load_lds_dwordx4 v[194:195], off
	s_add_i32 m0, s2, 0x2000
	v_lshl_add_u64 v[196:197], s[58:59], 0, v[202:203]
	global_load_lds_dwordx4 v[196:197], off
	s_add_u32 s2, s58, 0x80000
	s_addc_u32 s3, s59, 0
	v_lshl_add_u64 v[198:199], s[2:3], 0, v[206:207]
	s_add_i32 s43, s84, s66
	s_mov_b32 m0, s43
	s_nop 0
	global_load_lds_dwordx4 v[198:199], off
	v_lshl_add_u64 v[198:199], s[2:3], 0, v[202:203]
	s_add_i32 m0, s43, 0x2000
	s_nop 0
	global_load_lds_dwordx4 v[198:199], off
	v_lshl_add_u64 v[198:199], s[60:61], 0, v[208:209]
	s_mov_b32 m0, s55
	s_nop 0
	global_load_lds_dwordx4 v[198:199], off
	v_lshl_add_u64 v[200:201], s[60:61], 0, v[204:205]
	s_mov_b32 m0, s68
	s_nop 0
	global_load_lds_dwordx4 v[200:201], off
	s_setprio 1
	s_waitcnt vmcnt(8) lgkmcnt(0)
	s_barrier
	v_mfma_i32_16x16x64_i8 v[62:65], v[130:133], v[162:165], v[62:65]
	v_mfma_i32_16x16x64_i8 v[14:17], v[138:141], v[162:165], v[14:17]
	v_mfma_i32_16x16x64_i8 v[58:61], v[130:133], v[170:173], v[58:61]
	v_mfma_i32_16x16x64_i8 v[10:13], v[138:141], v[170:173], v[10:13]
	v_mfma_i32_16x16x64_i8 v[114:117], v[130:133], v[178:181], v[114:117]
	v_mfma_i32_16x16x64_i8 v[106:109], v[138:141], v[178:181], v[106:109]
	v_mfma_i32_16x16x64_i8 v[86:89], v[130:133], v[186:189], v[86:89]
	v_mfma_i32_16x16x64_i8 v[82:85], v[138:141], v[186:189], v[82:85]
	v_mfma_i32_16x16x64_i8 v[62:65], v[134:137], v[166:169], v[62:65]
	v_mfma_i32_16x16x64_i8 v[14:17], v[142:145], v[166:169], v[14:17]
	v_mfma_i32_16x16x64_i8 v[58:61], v[134:137], v[174:177], v[58:61]
	v_mfma_i32_16x16x64_i8 v[10:13], v[142:145], v[174:177], v[10:13]
	v_mfma_i32_16x16x64_i8 v[114:117], v[134:137], v[182:185], v[114:117]
	v_mfma_i32_16x16x64_i8 v[106:109], v[142:145], v[182:185], v[106:109]
	v_mfma_i32_16x16x64_i8 v[86:89], v[134:137], v[190:193], v[86:89]
	v_mfma_i32_16x16x64_i8 v[82:85], v[142:145], v[190:193], v[82:85]
	v_mfma_i32_16x16x64_i8 v[50:53], v[146:149], v[162:165], v[50:53]
	v_mfma_i32_16x16x64_i8 v[6:9], v[154:157], v[162:165], v[6:9]
	v_mfma_i32_16x16x64_i8 v[42:45], v[146:149], v[170:173], v[42:45]
	v_mfma_i32_16x16x64_i8 v[2:5], v[154:157], v[170:173], v[2:5]
	v_mfma_i32_16x16x64_i8 v[54:57], v[146:149], v[178:181], v[54:57]
	v_mfma_i32_16x16x64_i8 v[46:49], v[154:157], v[178:181], v[46:49]
	v_mfma_i32_16x16x64_i8 v[38:41], v[146:149], v[186:189], v[38:41]
	v_mfma_i32_16x16x64_i8 v[34:37], v[154:157], v[186:189], v[34:37]
	v_mfma_i32_16x16x64_i8 v[50:53], v[150:153], v[166:169], v[50:53]
	v_mfma_i32_16x16x64_i8 v[6:9], v[158:161], v[166:169], v[6:9]
	v_mfma_i32_16x16x64_i8 v[42:45], v[150:153], v[174:177], v[42:45]
	v_mfma_i32_16x16x64_i8 v[2:5], v[158:161], v[174:177], v[2:5]
	v_mfma_i32_16x16x64_i8 v[54:57], v[150:153], v[182:185], v[54:57]
	v_mfma_i32_16x16x64_i8 v[46:49], v[158:161], v[182:185], v[46:49]
	v_mfma_i32_16x16x64_i8 v[38:41], v[150:153], v[190:193], v[38:41]
	v_mfma_i32_16x16x64_i8 v[34:37], v[158:161], v[190:193], v[34:37]
	s_barrier
	s_setprio 0
	s_add_i32 s43, 0, 0x18000
	v_add_u32_e32 v142, s43, v237
	ds_read_b128 v[130:133], v142
	ds_read_b128 v[134:137], v142 offset:1024
	ds_read_b128 v[138:141], v142 offset:2048
	ds_read_b128 v[142:145], v142 offset:3072
	s_add_i32 s92, 0, 0x1c000
	v_add_u32_e32 v158, s92, v237
	ds_read_b128 v[146:149], v158
	ds_read_b128 v[150:153], v158 offset:1024
	ds_read_b128 v[154:157], v158 offset:2048
	ds_read_b128 v[158:161], v158 offset:3072
	ds_read_b128 v[162:165], v240 offset:32768
	ds_read_b128 v[166:169], v240 offset:33792
	ds_read_b128 v[170:173], v240 offset:34816
	ds_read_b128 v[174:177], v240 offset:35840
	ds_read_b128 v[178:181], v240 offset:36864
	ds_read_b128 v[182:185], v240 offset:37888
	ds_read_b128 v[186:189], v240 offset:38912
	ds_read_b128 v[190:193], v240 offset:39936
	s_mov_b32 m0, s69
	s_add_u32 s2, s60, 0x4000
	s_addc_u32 s3, s61, 0
	v_lshl_add_u64 v[220:221], s[2:3], 0, v[208:209]
	global_load_lds_dwordx4 v[220:221], off
	v_lshl_add_u64 v[220:221], s[2:3], 0, v[204:205]
	s_mov_b32 m0, s70
	s_nop 0
	global_load_lds_dwordx4 v[220:221], off
	s_setprio 1
	s_waitcnt vmcnt(8) lgkmcnt(0)
	s_barrier
	v_mfma_i32_16x16x64_i8 v[126:129], v[130:133], v[162:165], v[126:129]
	v_mfma_i32_16x16x64_i8 v[122:125], v[138:141], v[162:165], v[122:125]
	v_mfma_i32_16x16x64_i8 v[118:121], v[130:133], v[170:173], v[118:121]
	v_mfma_i32_16x16x64_i8 v[110:113], v[138:141], v[170:173], v[110:113]
	v_mfma_i32_16x16x64_i8 v[78:81], v[130:133], v[178:181], v[78:81]
	v_mfma_i32_16x16x64_i8 v[30:33], v[138:141], v[178:181], v[30:33]
	v_mfma_i32_16x16x64_i8 v[74:77], v[130:133], v[186:189], v[74:77]
	v_mfma_i32_16x16x64_i8 v[26:29], v[138:141], v[186:189], v[26:29]
	v_mfma_i32_16x16x64_i8 v[126:129], v[134:137], v[166:169], v[126:129]
	v_mfma_i32_16x16x64_i8 v[122:125], v[142:145], v[166:169], v[122:125]
	v_mfma_i32_16x16x64_i8 v[118:121], v[134:137], v[174:177], v[118:121]
	v_mfma_i32_16x16x64_i8 v[110:113], v[142:145], v[174:177], v[110:113]
	v_mfma_i32_16x16x64_i8 v[78:81], v[134:137], v[182:185], v[78:81]
	v_mfma_i32_16x16x64_i8 v[30:33], v[142:145], v[182:185], v[30:33]
	v_mfma_i32_16x16x64_i8 v[74:77], v[134:137], v[190:193], v[74:77]
	v_mfma_i32_16x16x64_i8 v[26:29], v[142:145], v[190:193], v[26:29]
	v_mfma_i32_16x16x64_i8 v[102:105], v[146:149], v[162:165], v[102:105]
	v_mfma_i32_16x16x64_i8 v[98:101], v[154:157], v[162:165], v[98:101]
	v_mfma_i32_16x16x64_i8 v[94:97], v[146:149], v[170:173], v[94:97]
	v_mfma_i32_16x16x64_i8 v[90:93], v[154:157], v[170:173], v[90:93]
	v_mfma_i32_16x16x64_i8 v[70:73], v[146:149], v[178:181], v[70:73]
	v_mfma_i32_16x16x64_i8 v[22:25], v[154:157], v[178:181], v[22:25]
	v_mfma_i32_16x16x64_i8 v[66:69], v[146:149], v[186:189], v[66:69]
	v_mfma_i32_16x16x64_i8 v[18:21], v[154:157], v[186:189], v[18:21]
	v_mfma_i32_16x16x64_i8 v[102:105], v[150:153], v[166:169], v[102:105]
	v_mfma_i32_16x16x64_i8 v[98:101], v[158:161], v[166:169], v[98:101]
	v_mfma_i32_16x16x64_i8 v[94:97], v[150:153], v[174:177], v[94:97]
	v_mfma_i32_16x16x64_i8 v[90:93], v[158:161], v[174:177], v[90:93]
	v_mfma_i32_16x16x64_i8 v[70:73], v[150:153], v[182:185], v[70:73]
	v_mfma_i32_16x16x64_i8 v[22:25], v[158:161], v[182:185], v[22:25]
	v_mfma_i32_16x16x64_i8 v[66:69], v[150:153], v[190:193], v[66:69]
	v_mfma_i32_16x16x64_i8 v[18:21], v[158:161], v[190:193], v[18:21]
	s_barrier
	s_setprio 0
	ds_read_b128 v[162:165], v240 offset:49152
	ds_read_b128 v[166:169], v240 offset:50176
	ds_read_b128 v[170:173], v240 offset:51200
	ds_read_b128 v[174:177], v240 offset:52224
	ds_read_b128 v[178:181], v240 offset:53248
	ds_read_b128 v[182:185], v240 offset:54272
	ds_read_b128 v[186:189], v240 offset:55296
	ds_read_b128 v[190:193], v240 offset:56320
	v_lshl_add_u64 v[194:195], v[194:195], 0, s[36:37]
	s_add_i32 s2, s43, s66
	s_mov_b32 m0, s2
	s_nop 0
	global_load_lds_dwordx4 v[194:195], off
	s_add_i32 m0, s2, 0x2000
	v_lshl_add_u64 v[194:195], v[196:197], 0, s[36:37]
	global_load_lds_dwordx4 v[194:195], off
	s_add_u32 s2, s58, 0x80080
	s_addc_u32 s3, s59, 0
	v_lshl_add_u64 v[194:195], s[2:3], 0, v[206:207]
	s_add_i32 s43, s92, s66
	s_mov_b32 m0, s43
	s_nop 0
	global_load_lds_dwordx4 v[194:195], off
	v_lshl_add_u64 v[194:195], s[2:3], 0, v[202:203]
	s_add_i32 m0, s43, 0x2000
	s_nop 0
	global_load_lds_dwordx4 v[194:195], off
	v_lshl_add_u64 v[194:195], v[198:199], 0, s[36:37]
	s_mov_b32 m0, s77
	s_nop 0
	global_load_lds_dwordx4 v[194:195], off
	v_lshl_add_u64 v[194:195], v[200:201], 0, s[36:37]
	s_mov_b32 m0, s78
	s_nop 0
	global_load_lds_dwordx4 v[194:195], off
	s_setprio 1
	s_waitcnt vmcnt(8) lgkmcnt(0)
	s_barrier
	v_mfma_i32_16x16x64_i8 v[62:65], v[130:133], v[162:165], v[62:65]
	v_mfma_i32_16x16x64_i8 v[14:17], v[138:141], v[162:165], v[14:17]
	v_mfma_i32_16x16x64_i8 v[58:61], v[130:133], v[170:173], v[58:61]
	v_mfma_i32_16x16x64_i8 v[10:13], v[138:141], v[170:173], v[10:13]
	v_mfma_i32_16x16x64_i8 v[114:117], v[130:133], v[178:181], v[114:117]
	v_mfma_i32_16x16x64_i8 v[106:109], v[138:141], v[178:181], v[106:109]
	v_mfma_i32_16x16x64_i8 v[86:89], v[130:133], v[186:189], v[86:89]
	v_mfma_i32_16x16x64_i8 v[82:85], v[138:141], v[186:189], v[82:85]
	v_mfma_i32_16x16x64_i8 v[62:65], v[134:137], v[166:169], v[62:65]
	v_mfma_i32_16x16x64_i8 v[14:17], v[142:145], v[166:169], v[14:17]
	v_mfma_i32_16x16x64_i8 v[58:61], v[134:137], v[174:177], v[58:61]
	v_mfma_i32_16x16x64_i8 v[10:13], v[142:145], v[174:177], v[10:13]
	v_mfma_i32_16x16x64_i8 v[114:117], v[134:137], v[182:185], v[114:117]
	v_mfma_i32_16x16x64_i8 v[106:109], v[142:145], v[182:185], v[106:109]
	v_mfma_i32_16x16x64_i8 v[86:89], v[134:137], v[190:193], v[86:89]
	v_mfma_i32_16x16x64_i8 v[82:85], v[142:145], v[190:193], v[82:85]
	v_mfma_i32_16x16x64_i8 v[50:53], v[146:149], v[162:165], v[50:53]
	v_mfma_i32_16x16x64_i8 v[6:9], v[154:157], v[162:165], v[6:9]
	v_mfma_i32_16x16x64_i8 v[42:45], v[146:149], v[170:173], v[42:45]
	v_mfma_i32_16x16x64_i8 v[2:5], v[154:157], v[170:173], v[2:5]
	v_mfma_i32_16x16x64_i8 v[54:57], v[146:149], v[178:181], v[54:57]
	v_mfma_i32_16x16x64_i8 v[46:49], v[154:157], v[178:181], v[46:49]
	v_mfma_i32_16x16x64_i8 v[38:41], v[146:149], v[186:189], v[38:41]
	v_mfma_i32_16x16x64_i8 v[34:37], v[154:157], v[186:189], v[34:37]
	v_mfma_i32_16x16x64_i8 v[50:53], v[150:153], v[166:169], v[50:53]
	v_mfma_i32_16x16x64_i8 v[6:9], v[158:161], v[166:169], v[6:9]
	v_mfma_i32_16x16x64_i8 v[42:45], v[150:153], v[174:177], v[42:45]
	v_mfma_i32_16x16x64_i8 v[2:5], v[158:161], v[174:177], v[2:5]
	v_mfma_i32_16x16x64_i8 v[54:57], v[150:153], v[182:185], v[54:57]
	v_mfma_i32_16x16x64_i8 v[46:49], v[158:161], v[182:185], v[46:49]
	v_mfma_i32_16x16x64_i8 v[38:41], v[150:153], v[190:193], v[38:41]
	v_mfma_i32_16x16x64_i8 v[34:37], v[158:161], v[190:193], v[34:37]
	s_barrier
	s_setprio 0
	s_add_i32 s91, s91, 2
	s_add_u32 s89, s89, 0x100
	s_addc_u32 s90, s90, 0
	s_cmp_gt_u32 s91, 29
	s_mov_b64 s[2:3], s[56:57]
	s_cbranch_scc0 .LBB0_1697
	s_and_b64 vcc, exec, s[38:39]
	s_cbranch_vccz .LBB0_1700
	s_barrier

.LBB0_1951:
	ds_read_b128 v[130:133], v167
	ds_read_b128 v[134:137], v167 offset:1024
	ds_read_b128 v[138:141], v167 offset:2048
	ds_read_b128 v[142:145], v167 offset:3072
	ds_read_b128 v[170:173], v168
	ds_read_b128 v[174:177], v168 offset:1024
	ds_read_b128 v[178:181], v168 offset:2048
	ds_read_b128 v[182:185], v168 offset:3072
	ds_read_b128 v[186:189], v169
	ds_read_b128 v[190:193], v169 offset:1024
	ds_read_b128 v[194:197], v169 offset:2048
	ds_read_b128 v[198:201], v169 offset:3072
	ds_read_b128 v[202:205], v169 offset:4096
	ds_read_b128 v[206:209], v169 offset:5120
	ds_read_b128 v[210:213], v169 offset:6144
	ds_read_b128 v[214:217], v169 offset:7168
	v_lshl_add_u64 v[162:163], s[36:37], 0, v[154:155]
	s_add_i32 m0, s52, 0xc000
	s_nop 0
	global_load_lds_dwordx4 v[162:163], off
	v_lshl_add_u64 v[162:163], s[36:37], 0, v[156:157]
	s_add_i32 m0, s52, 0xe000
	s_nop 0
	global_load_lds_dwordx4 v[162:163], off
	s_add_u32 s38, s36, 0x100
	s_addc_u32 s39, s37, 0
	s_cmpk_eq_i32 s77, 0x52
	s_cselect_b32 s47, s3, s39
	s_cselect_b32 s46, s2, s38
	s_cselect_b32 s45, s35, s76
	s_cselect_b32 s44, s34, s75
	s_setprio 1
	s_waitcnt vmcnt(8) lgkmcnt(0)
	s_barrier
	v_mfma_i32_16x16x64_i8 v[126:129], v[130:133], v[186:189], v[126:129]
	v_mfma_i32_16x16x64_i8 v[122:125], v[138:141], v[186:189], v[122:125]
	v_mfma_i32_16x16x64_i8 v[110:113], v[130:133], v[194:197], v[110:113]
	v_mfma_i32_16x16x64_i8 v[106:109], v[138:141], v[194:197], v[106:109]
	v_mfma_i32_16x16x64_i8 v[94:97], v[130:133], v[202:205], v[94:97]
	v_mfma_i32_16x16x64_i8 v[90:93], v[138:141], v[202:205], v[90:93]
	v_mfma_i32_16x16x64_i8 v[78:81], v[130:133], v[210:213], v[78:81]
	v_mfma_i32_16x16x64_i8 v[74:77], v[138:141], v[210:213], v[74:77]
	v_mfma_i32_16x16x64_i8 v[126:129], v[134:137], v[190:193], v[126:129]
	v_mfma_i32_16x16x64_i8 v[122:125], v[142:145], v[190:193], v[122:125]
	v_mfma_i32_16x16x64_i8 v[110:113], v[134:137], v[198:201], v[110:113]
	v_mfma_i32_16x16x64_i8 v[106:109], v[142:145], v[198:201], v[106:109]
	v_mfma_i32_16x16x64_i8 v[94:97], v[134:137], v[206:209], v[94:97]
	v_mfma_i32_16x16x64_i8 v[90:93], v[142:145], v[206:209], v[90:93]
	v_mfma_i32_16x16x64_i8 v[78:81], v[134:137], v[214:217], v[78:81]
	v_mfma_i32_16x16x64_i8 v[74:77], v[142:145], v[214:217], v[74:77]
	v_mfma_i32_16x16x64_i8 v[118:121], v[170:173], v[186:189], v[118:121]
	v_mfma_i32_16x16x64_i8 v[114:117], v[178:181], v[186:189], v[114:117]
	v_mfma_i32_16x16x64_i8 v[102:105], v[170:173], v[194:197], v[102:105]
	v_mfma_i32_16x16x64_i8 v[98:101], v[178:181], v[194:197], v[98:101]
	v_mfma_i32_16x16x64_i8 v[86:89], v[170:173], v[202:205], v[86:89]
	v_mfma_i32_16x16x64_i8 v[82:85], v[178:181], v[202:205], v[82:85]
	v_mfma_i32_16x16x64_i8 v[70:73], v[170:173], v[210:213], v[70:73]
	v_mfma_i32_16x16x64_i8 v[66:69], v[178:181], v[210:213], v[66:69]
	v_mfma_i32_16x16x64_i8 v[118:121], v[174:177], v[190:193], v[118:121]
	v_mfma_i32_16x16x64_i8 v[114:117], v[182:185], v[190:193], v[114:117]
	v_mfma_i32_16x16x64_i8 v[102:105], v[174:177], v[198:201], v[102:105]
	v_mfma_i32_16x16x64_i8 v[98:101], v[182:185], v[198:201], v[98:101]
	v_mfma_i32_16x16x64_i8 v[86:89], v[174:177], v[206:209], v[86:89]
	v_mfma_i32_16x16x64_i8 v[82:85], v[182:185], v[206:209], v[82:85]
	v_mfma_i32_16x16x64_i8 v[70:73], v[174:177], v[214:217], v[70:73]
	v_mfma_i32_16x16x64_i8 v[66:69], v[182:185], v[214:217], v[66:69]
	s_barrier
	s_setprio 0
	ds_read_b128 v[186:189], v169 offset:16384
	ds_read_b128 v[190:193], v169 offset:17408
	ds_read_b128 v[194:197], v169 offset:18432
	ds_read_b128 v[198:201], v169 offset:19456
	ds_read_b128 v[202:205], v169 offset:20480
	ds_read_b128 v[206:209], v169 offset:21504
	ds_read_b128 v[210:213], v169 offset:22528
	ds_read_b128 v[214:217], v169 offset:23552
	v_lshl_add_u64 v[162:163], s[44:45], 0, v[150:151]
	s_add_i32 s36, s61, s51
	s_mov_b32 m0, s36
	s_nop 0
	global_load_lds_dwordx4 v[162:163], off
	s_add_i32 m0, s36, 0x2000
	v_lshl_add_u64 v[218:219], s[44:45], 0, v[146:147]
	global_load_lds_dwordx4 v[218:219], off
	s_add_u32 s36, s44, 0x158000
	s_addc_u32 s37, s45, 0
	v_lshl_add_u64 v[220:221], s[36:37], 0, v[150:151]
	s_add_i32 s78, s62, s51
	s_mov_b32 m0, s78
	s_nop 0
	global_load_lds_dwordx4 v[220:221], off
	v_lshl_add_u64 v[220:221], s[36:37], 0, v[146:147]
	s_add_i32 m0, s78, 0x2000
	s_nop 0
	global_load_lds_dwordx4 v[220:221], off
	v_lshl_add_u64 v[220:221], s[46:47], 0, v[152:153]
	s_mov_b32 m0, s52
	s_nop 0
	global_load_lds_dwordx4 v[220:221], off
	v_lshl_add_u64 v[222:223], s[46:47], 0, v[148:149]
	s_mov_b32 m0, s53
	s_nop 0
	global_load_lds_dwordx4 v[222:223], off
	s_setprio 1
	s_waitcnt vmcnt(8) lgkmcnt(0)
	s_barrier
	v_mfma_i32_16x16x64_i8 v[62:65], v[130:133], v[186:189], v[62:65]
	v_mfma_i32_16x16x64_i8 v[58:61], v[138:141], v[186:189], v[58:61]
	v_mfma_i32_16x16x64_i8 v[46:49], v[130:133], v[194:197], v[46:49]
	v_mfma_i32_16x16x64_i8 v[42:45], v[138:141], v[194:197], v[42:45]
	v_mfma_i32_16x16x64_i8 v[30:33], v[130:133], v[202:205], v[30:33]
	v_mfma_i32_16x16x64_i8 v[26:29], v[138:141], v[202:205], v[26:29]
	v_mfma_i32_16x16x64_i8 v[14:17], v[130:133], v[210:213], v[14:17]
	v_mfma_i32_16x16x64_i8 v[10:13], v[138:141], v[210:213], v[10:13]
	v_mfma_i32_16x16x64_i8 v[62:65], v[134:137], v[190:193], v[62:65]
	v_mfma_i32_16x16x64_i8 v[58:61], v[142:145], v[190:193], v[58:61]
	v_mfma_i32_16x16x64_i8 v[46:49], v[134:137], v[198:201], v[46:49]
	v_mfma_i32_16x16x64_i8 v[42:45], v[142:145], v[198:201], v[42:45]
	v_mfma_i32_16x16x64_i8 v[30:33], v[134:137], v[206:209], v[30:33]
	v_mfma_i32_16x16x64_i8 v[26:29], v[142:145], v[206:209], v[26:29]
	v_mfma_i32_16x16x64_i8 v[14:17], v[134:137], v[214:217], v[14:17]
	v_mfma_i32_16x16x64_i8 v[10:13], v[142:145], v[214:217], v[10:13]
	v_mfma_i32_16x16x64_i8 v[54:57], v[170:173], v[186:189], v[54:57]
	v_mfma_i32_16x16x64_i8 v[50:53], v[178:181], v[186:189], v[50:53]
	v_mfma_i32_16x16x64_i8 v[38:41], v[170:173], v[194:197], v[38:41]
	v_mfma_i32_16x16x64_i8 v[34:37], v[178:181], v[194:197], v[34:37]
	v_mfma_i32_16x16x64_i8 v[22:25], v[170:173], v[202:205], v[22:25]
	v_mfma_i32_16x16x64_i8 v[18:21], v[178:181], v[202:205], v[18:21]
	v_mfma_i32_16x16x64_i8 v[6:9], v[170:173], v[210:213], v[6:9]
	v_mfma_i32_16x16x64_i8 v[2:5], v[178:181], v[210:213], v[2:5]
	v_mfma_i32_16x16x64_i8 v[54:57], v[174:177], v[190:193], v[54:57]
	v_mfma_i32_16x16x64_i8 v[50:53], v[182:185], v[190:193], v[50:53]
	v_mfma_i32_16x16x64_i8 v[38:41], v[174:177], v[198:201], v[38:41]
	v_mfma_i32_16x16x64_i8 v[34:37], v[182:185], v[198:201], v[34:37]
	v_mfma_i32_16x16x64_i8 v[22:25], v[174:177], v[206:209], v[22:25]
	v_mfma_i32_16x16x64_i8 v[18:21], v[182:185], v[206:209], v[18:21]
	v_mfma_i32_16x16x64_i8 v[6:9], v[174:177], v[214:217], v[6:9]
	v_mfma_i32_16x16x64_i8 v[2:5], v[182:185], v[214:217], v[2:5]
	s_barrier
	s_setprio 0
	s_add_i32 s78, 0, 0x18000
	v_add_u32_e32 v142, s78, v166
	ds_read_b128 v[130:133], v142
	ds_read_b128 v[134:137], v142 offset:1024
	ds_read_b128 v[138:141], v142 offset:2048
	ds_read_b128 v[142:145], v142 offset:3072
	s_add_i32 s79, 0, 0x1c000
	v_add_u32_e32 v182, s79, v166
	ds_read_b128 v[170:173], v182
	ds_read_b128 v[174:177], v182 offset:1024
	ds_read_b128 v[178:181], v182 offset:2048
	ds_read_b128 v[182:185], v182 offset:3072
	ds_read_b128 v[186:189], v169 offset:32768
	ds_read_b128 v[190:193], v169 offset:33792
	ds_read_b128 v[194:197], v169 offset:34816
	ds_read_b128 v[198:201], v169 offset:35840
	ds_read_b128 v[202:205], v169 offset:36864
	ds_read_b128 v[206:209], v169 offset:37888
	ds_read_b128 v[210:213], v169 offset:38912
	ds_read_b128 v[214:217], v169 offset:39936
	s_mov_b32 m0, s54
	s_add_u32 s36, s46, 0x158000
	s_addc_u32 s37, s47, 0
	v_lshl_add_u64 v[224:225], s[36:37], 0, v[152:153]
	global_load_lds_dwordx4 v[224:225], off
	v_lshl_add_u64 v[224:225], s[36:37], 0, v[148:149]
	s_mov_b32 m0, s55
	s_nop 0
	global_load_lds_dwordx4 v[224:225], off
	s_setprio 1
	s_waitcnt vmcnt(8) lgkmcnt(0)
	s_barrier
	v_mfma_i32_16x16x64_i8 v[126:129], v[130:133], v[186:189], v[126:129]
	v_mfma_i32_16x16x64_i8 v[122:125], v[138:141], v[186:189], v[122:125]
	v_mfma_i32_16x16x64_i8 v[110:113], v[130:133], v[194:197], v[110:113]
	v_mfma_i32_16x16x64_i8 v[106:109], v[138:141], v[194:197], v[106:109]
	v_mfma_i32_16x16x64_i8 v[94:97], v[130:133], v[202:205], v[94:97]
	v_mfma_i32_16x16x64_i8 v[90:93], v[138:141], v[202:205], v[90:93]
	v_mfma_i32_16x16x64_i8 v[78:81], v[130:133], v[210:213], v[78:81]
	v_mfma_i32_16x16x64_i8 v[74:77], v[138:141], v[210:213], v[74:77]
	v_mfma_i32_16x16x64_i8 v[126:129], v[134:137], v[190:193], v[126:129]
	v_mfma_i32_16x16x64_i8 v[122:125], v[142:145], v[190:193], v[122:125]
	v_mfma_i32_16x16x64_i8 v[110:113], v[134:137], v[198:201], v[110:113]
	v_mfma_i32_16x16x64_i8 v[106:109], v[142:145], v[198:201], v[106:109]
	v_mfma_i32_16x16x64_i8 v[94:97], v[134:137], v[206:209], v[94:97]
	v_mfma_i32_16x16x64_i8 v[90:93], v[142:145], v[206:209], v[90:93]
	v_mfma_i32_16x16x64_i8 v[78:81], v[134:137], v[214:217], v[78:81]
	v_mfma_i32_16x16x64_i8 v[74:77], v[142:145], v[214:217], v[74:77]
	v_mfma_i32_16x16x64_i8 v[118:121], v[170:173], v[186:189], v[118:121]
	v_mfma_i32_16x16x64_i8 v[114:117], v[178:181], v[186:189], v[114:117]
	v_mfma_i32_16x16x64_i8 v[102:105], v[170:173], v[194:197], v[102:105]
	v_mfma_i32_16x16x64_i8 v[98:101], v[178:181], v[194:197], v[98:101]
	v_mfma_i32_16x16x64_i8 v[86:89], v[170:173], v[202:205], v[86:89]
	v_mfma_i32_16x16x64_i8 v[82:85], v[178:181], v[202:205], v[82:85]
	v_mfma_i32_16x16x64_i8 v[70:73], v[170:173], v[210:213], v[70:73]
	v_mfma_i32_16x16x64_i8 v[66:69], v[178:181], v[210:213], v[66:69]
	v_mfma_i32_16x16x64_i8 v[118:121], v[174:177], v[190:193], v[118:121]
	v_mfma_i32_16x16x64_i8 v[114:117], v[182:185], v[190:193], v[114:117]
	v_mfma_i32_16x16x64_i8 v[102:105], v[174:177], v[198:201], v[102:105]
	v_mfma_i32_16x16x64_i8 v[98:101], v[182:185], v[198:201], v[98:101]
	v_mfma_i32_16x16x64_i8 v[86:89], v[174:177], v[206:209], v[86:89]
	v_mfma_i32_16x16x64_i8 v[82:85], v[182:185], v[206:209], v[82:85]
	v_mfma_i32_16x16x64_i8 v[70:73], v[174:177], v[214:217], v[70:73]
	v_mfma_i32_16x16x64_i8 v[66:69], v[182:185], v[214:217], v[66:69]
	s_barrier
	s_setprio 0
	ds_read_b128 v[186:189], v169 offset:49152
	ds_read_b128 v[190:193], v169 offset:50176
	ds_read_b128 v[194:197], v169 offset:51200
	ds_read_b128 v[198:201], v169 offset:52224
	ds_read_b128 v[202:205], v169 offset:53248
	ds_read_b128 v[206:209], v169 offset:54272
	ds_read_b128 v[210:213], v169 offset:55296
	ds_read_b128 v[214:217], v169 offset:56320
	v_lshl_add_u64 v[162:163], v[162:163], 0, s[14:15]
	s_add_i32 s36, s78, s51
	s_mov_b32 m0, s36
	s_nop 0
	global_load_lds_dwordx4 v[162:163], off
	s_add_i32 m0, s36, 0x2000
	v_lshl_add_u64 v[162:163], v[218:219], 0, s[14:15]
	global_load_lds_dwordx4 v[162:163], off
	s_add_u32 s36, s44, 0x158080
	s_addc_u32 s37, s45, 0
	v_lshl_add_u64 v[162:163], s[36:37], 0, v[150:151]
	s_add_i32 s44, s79, s51
	s_mov_b32 m0, s44
	s_nop 0
	global_load_lds_dwordx4 v[162:163], off
	v_lshl_add_u64 v[162:163], s[36:37], 0, v[146:147]
	s_add_i32 m0, s44, 0x2000
	s_nop 0
	global_load_lds_dwordx4 v[162:163], off
	v_lshl_add_u64 v[162:163], v[220:221], 0, s[14:15]
	s_mov_b32 m0, s59
	s_nop 0
	global_load_lds_dwordx4 v[162:163], off
	v_lshl_add_u64 v[162:163], v[222:223], 0, s[14:15]
	s_mov_b32 m0, s60
	s_nop 0
	global_load_lds_dwordx4 v[162:163], off
	s_setprio 1
	s_waitcnt vmcnt(8) lgkmcnt(0)
	s_barrier
	v_mfma_i32_16x16x64_i8 v[62:65], v[130:133], v[186:189], v[62:65]
	v_mfma_i32_16x16x64_i8 v[58:61], v[138:141], v[186:189], v[58:61]
	v_mfma_i32_16x16x64_i8 v[46:49], v[130:133], v[194:197], v[46:49]
	v_mfma_i32_16x16x64_i8 v[42:45], v[138:141], v[194:197], v[42:45]
	v_mfma_i32_16x16x64_i8 v[30:33], v[130:133], v[202:205], v[30:33]
	v_mfma_i32_16x16x64_i8 v[26:29], v[138:141], v[202:205], v[26:29]
	v_mfma_i32_16x16x64_i8 v[14:17], v[130:133], v[210:213], v[14:17]
	v_mfma_i32_16x16x64_i8 v[10:13], v[138:141], v[210:213], v[10:13]
	v_mfma_i32_16x16x64_i8 v[62:65], v[134:137], v[190:193], v[62:65]
	v_mfma_i32_16x16x64_i8 v[58:61], v[142:145], v[190:193], v[58:61]
	v_mfma_i32_16x16x64_i8 v[46:49], v[134:137], v[198:201], v[46:49]
	v_mfma_i32_16x16x64_i8 v[42:45], v[142:145], v[198:201], v[42:45]
	v_mfma_i32_16x16x64_i8 v[30:33], v[134:137], v[206:209], v[30:33]
	v_mfma_i32_16x16x64_i8 v[26:29], v[142:145], v[206:209], v[26:29]
	v_mfma_i32_16x16x64_i8 v[14:17], v[134:137], v[214:217], v[14:17]
	v_mfma_i32_16x16x64_i8 v[10:13], v[142:145], v[214:217], v[10:13]
	v_mfma_i32_16x16x64_i8 v[54:57], v[170:173], v[186:189], v[54:57]
	v_mfma_i32_16x16x64_i8 v[50:53], v[178:181], v[186:189], v[50:53]
	v_mfma_i32_16x16x64_i8 v[38:41], v[170:173], v[194:197], v[38:41]
	v_mfma_i32_16x16x64_i8 v[34:37], v[178:181], v[194:197], v[34:37]
	v_mfma_i32_16x16x64_i8 v[22:25], v[170:173], v[202:205], v[22:25]
	v_mfma_i32_16x16x64_i8 v[18:21], v[178:181], v[202:205], v[18:21]
	v_mfma_i32_16x16x64_i8 v[6:9], v[170:173], v[210:213], v[6:9]
	v_mfma_i32_16x16x64_i8 v[2:5], v[178:181], v[210:213], v[2:5]
	v_mfma_i32_16x16x64_i8 v[54:57], v[174:177], v[190:193], v[54:57]
	v_mfma_i32_16x16x64_i8 v[50:53], v[182:185], v[190:193], v[50:53]
	v_mfma_i32_16x16x64_i8 v[38:41], v[174:177], v[198:201], v[38:41]
	v_mfma_i32_16x16x64_i8 v[34:37], v[182:185], v[198:201], v[34:37]
	v_mfma_i32_16x16x64_i8 v[22:25], v[174:177], v[206:209], v[22:25]
	v_mfma_i32_16x16x64_i8 v[18:21], v[182:185], v[206:209], v[18:21]
	v_mfma_i32_16x16x64_i8 v[6:9], v[174:177], v[214:217], v[6:9]
	v_mfma_i32_16x16x64_i8 v[2:5], v[182:185], v[214:217], v[2:5]
	s_barrier
	s_setprio 0
	s_add_i32 s77, s77, 2
	s_add_u32 s75, s75, 0x100
	s_addc_u32 s76, s76, 0
	s_cmpk_gt_u32 s77, 0x53
	s_mov_b64 s[36:37], s[38:39]
	s_cbranch_scc0 .LBB0_1951
	s_and_b64 vcc, exec, s[16:17]
	s_cbranch_vccz .LBB0_1954
	s_barrier
